# GEMM main loops: all per-phase s_setprio flips removed (MFMA phase is the critical path; testing whether the priority flips pay for their issue slots)
# baseline (speedup 1.0000x reference)
; #define PG8_STAGE(bufoff, gbase, voff) do { _Pragma("unroll") for (int _i = 0; _i < 2; ++_i) \
;         __builtin_amdgcn_global_load_lds((const unsigned*)((const char*)(gbase) + (voff)[_i]), (LAS unsigned*)(lds + (bufoff) + ldsw + _i * 8192), 16, 0, 0); } while (0)
; #define PG8_LDA(dst, b, h) do { _Pragma("unroll") for (int m = 0; m < 4; ++m) _Pragma("unroll") for (int k = 0; k < 2; ++k) dst[m][k] = *(const LAS bf16x8*)(lds + PG8_SA(b, h) + aoff + m * 2048 + k * 1024); } while (0)
; #define PG8_LDB(dst, b, h) do { _Pragma("unroll") for (int n = 0; n < 2; ++n) _Pragma("unroll") for (int k = 0; k < 2; ++k) dst[n][k] = *(const LAS bf16x8*)(lds + PG8_SB(b, h) + boff + n * 2048 + k * 1024); } while (0)
; #define PG8_MMA(ai, bj, At, Bt) do { __builtin_amdgcn_s_setprio(1); _Pragma("unroll") for (int m = 0; m < 4; ++m) _Pragma("unroll") for (int n = 0; n < 2; ++n) _Pragma("unroll") for (int k = 0; k < 2; ++k) \
;         acc[ai][bj][m][n] = __builtin_amdgcn_mfma_f32_16x16x32_bf16(Bt[n][k], At[m][k], acc[ai][bj][m][n], 0, 0, 0); __builtin_amdgcn_s_setprio(0); } while (0)
; #define PG8_WAIT_V(n) asm volatile("s_waitcnt vmcnt(" #n ")" ::: "memory")
; #define PG8_WAIT_L(n) asm volatile("s_waitcnt lgkmcnt(" #n ")" ::: "memory")
; #define PG8_BAR __builtin_amdgcn_s_barrier()
; #define PG8_SCHED __builtin_amdgcn_sched_barrier(0)
; template <class Epi>
; __device__ __forceinline__ void gemm_phase(LAS unsigned char* lds, const Gemm g, const StaticOrder& S, const Epi& E) {
;     ...
;         for (int t = 0; t < nt; t += 2) {
;             const bool last = (t == nt - 2);
;             const char* a1 = cA + (size_t)(t + 1) * kstep;
;             const char* a2 = last ? nA : cA + (size_t)(t + 2) * kstep; const char* b2 = last ? nB : cB + (size_t)(t + 2) * kstep;
;             const char* a3 = a2 + kstep; const char* b3 = b2 + kstep;
;             PG8_LDB(B0, 0, 0); PG8_LDB(B1, 0, 1); PG8_SCHED; PG8_LDA(At, 0, 0); PG8_STAGE(PG8_SA(1, 1), a1 + hA, voffA);
;             PG8_WAIT_V(8); PG8_WAIT_L(0); PG8_BAR; PG8_MMA(0, 0, At, B0); PG8_MMA(0, 1, At, B1); PG8_BAR; PG8_SCHED;
;             PG8_LDA(At, 0, 1); PG8_STAGE(PG8_SB(0, 0), b2, voffB); PG8_STAGE(PG8_SB(0, 1), b2 + hB, voffB); PG8_STAGE(PG8_SA(0, 0), a2, voffA);
;             PG8_WAIT_V(8); PG8_WAIT_L(0); PG8_BAR; PG8_MMA(1, 0, At, B0); PG8_MMA(1, 1, At, B1); PG8_BAR; PG8_SCHED;
.LBB0_132:
	s_add_u32 s34, s8, 0xfffc0080
	s_addc_u32 s35, s9, -1
	s_add_i32 s42, 0, 0x10000
	s_cmp_eq_u32 s41, 12
	s_cselect_b32 s37, s7, s35
	s_cselect_b32 s36, s27, s34
	v_add_u32_e32 v153, s42, v139
	s_cselect_b32 s35, s25, s40
	s_cselect_b32 s34, s38, s39
	s_add_i32 s44, 0, 0x14000
	ds_read_b128 v[166:169], v153
	ds_read_b128 v[170:173], v153 offset:1024
	ds_read_b128 v[174:177], v153 offset:2048
	ds_read_b128 v[182:185], v153 offset:3072
	v_add_u32_e32 v153, s44, v139
	ds_read_b128 v[186:189], v153
	ds_read_b128 v[190:193], v153 offset:1024
	ds_read_b128 v[194:197], v153 offset:2048
	ds_read_b128 v[198:201], v153 offset:3072
	v_lshl_add_u64 v[178:179], s[8:9], 0, v[162:163]
	s_add_i32 m0, s19, 0xc000
	ds_read_b128 v[202:205], v149
	ds_read_b128 v[206:209], v149 offset:1024
	ds_read_b128 v[210:213], v149 offset:2048
	ds_read_b128 v[214:217], v149 offset:3072
	ds_read_b128 v[218:221], v149 offset:4096
	ds_read_b128 v[232:235], v149 offset:5120
	ds_read_b128 v[236:239], v149 offset:6144
	ds_read_b128 v[240:243], v149 offset:7168
	global_load_lds_dwordx4 v[178:179], off
	v_lshl_add_u64 v[178:179], s[8:9], 0, v[164:165]
	s_add_i32 m0, s19, 0xe000
	s_nop 0
	global_load_lds_dwordx4 v[178:179], off
	s_waitcnt vmcnt(8)
	s_waitcnt lgkmcnt(0)
	s_barrier
	v_mfma_f32_16x16x32_bf16 v[126:129], v[166:169], v[202:205], v[126:129]
	v_mfma_f32_16x16x32_bf16 v[122:125], v[174:177], v[202:205], v[122:125]
	v_mfma_f32_16x16x32_bf16 v[110:113], v[166:169], v[210:213], v[110:113]
	v_mfma_f32_16x16x32_bf16 v[106:109], v[174:177], v[210:213], v[106:109]
	v_mfma_f32_16x16x32_bf16 v[94:97], v[166:169], v[218:221], v[94:97]
	v_mfma_f32_16x16x32_bf16 v[90:93], v[174:177], v[218:221], v[90:93]
	v_mfma_f32_16x16x32_bf16 v[78:81], v[166:169], v[236:239], v[78:81]
	v_mfma_f32_16x16x32_bf16 v[74:77], v[174:177], v[236:239], v[74:77]
	v_mfma_f32_16x16x32_bf16 v[126:129], v[170:173], v[206:209], v[126:129]
	v_mfma_f32_16x16x32_bf16 v[122:125], v[182:185], v[206:209], v[122:125]
	v_mfma_f32_16x16x32_bf16 v[110:113], v[170:173], v[214:217], v[110:113]
	v_mfma_f32_16x16x32_bf16 v[106:109], v[182:185], v[214:217], v[106:109]
	v_mfma_f32_16x16x32_bf16 v[94:97], v[170:173], v[232:235], v[94:97]
	v_mfma_f32_16x16x32_bf16 v[90:93], v[182:185], v[232:235], v[90:93]
	v_mfma_f32_16x16x32_bf16 v[78:81], v[170:173], v[240:243], v[78:81]
	v_mfma_f32_16x16x32_bf16 v[74:77], v[182:185], v[240:243], v[74:77]
	v_mfma_f32_16x16x32_bf16 v[118:121], v[186:189], v[202:205], v[118:121]
	v_mfma_f32_16x16x32_bf16 v[114:117], v[194:197], v[202:205], v[114:117]
	v_mfma_f32_16x16x32_bf16 v[102:105], v[186:189], v[210:213], v[102:105]
	v_mfma_f32_16x16x32_bf16 v[98:101], v[194:197], v[210:213], v[98:101]
	v_mfma_f32_16x16x32_bf16 v[86:89], v[186:189], v[218:221], v[86:89]
	v_mfma_f32_16x16x32_bf16 v[82:85], v[194:197], v[218:221], v[82:85]
	v_mfma_f32_16x16x32_bf16 v[70:73], v[186:189], v[236:239], v[70:73]
	v_mfma_f32_16x16x32_bf16 v[66:69], v[194:197], v[236:239], v[66:69]
	v_mfma_f32_16x16x32_bf16 v[118:121], v[190:193], v[206:209], v[118:121]
	v_mfma_f32_16x16x32_bf16 v[114:117], v[198:201], v[206:209], v[114:117]
	v_mfma_f32_16x16x32_bf16 v[102:105], v[190:193], v[214:217], v[102:105]
	v_mfma_f32_16x16x32_bf16 v[98:101], v[198:201], v[214:217], v[98:101]
	v_mfma_f32_16x16x32_bf16 v[86:89], v[190:193], v[232:235], v[86:89]
	v_mfma_f32_16x16x32_bf16 v[82:85], v[198:201], v[232:235], v[82:85]
	v_mfma_f32_16x16x32_bf16 v[70:73], v[190:193], v[240:243], v[70:73]
	v_mfma_f32_16x16x32_bf16 v[66:69], v[198:201], v[240:243], v[66:69]
	s_barrier
	s_add_i32 s42, s42, s51
	v_lshl_add_u64 v[178:179], s[34:35], 0, v[132:133]
	s_mov_b32 m0, s42
	ds_read_b128 v[202:205], v149 offset:16384
	ds_read_b128 v[206:209], v149 offset:17408
	ds_read_b128 v[210:213], v149 offset:18432
	ds_read_b128 v[214:217], v149 offset:19456
	ds_read_b128 v[218:221], v149 offset:20480
	ds_read_b128 v[232:235], v149 offset:21504
	ds_read_b128 v[236:239], v149 offset:22528
	ds_read_b128 v[240:243], v149 offset:23552
	global_load_lds_dwordx4 v[178:179], off
	s_add_i32 m0, s42, 0x2000
	s_add_u32 s42, s34, 0x40000
	v_lshl_add_u64 v[244:245], s[34:35], 0, v[136:137]
	s_addc_u32 s43, s35, 0
	s_add_i32 s44, s44, s51
	global_load_lds_dwordx4 v[244:245], off
	v_lshl_add_u64 v[246:247], s[42:43], 0, v[132:133]
	s_mov_b32 m0, s44
	v_lshl_add_u64 v[248:249], s[36:37], 0, v[134:135]
	global_load_lds_dwordx4 v[246:247], off
	v_lshl_add_u64 v[246:247], s[42:43], 0, v[136:137]
	s_add_i32 m0, s44, 0x2000
	s_nop 0
	global_load_lds_dwordx4 v[246:247], off
	v_lshl_add_u64 v[246:247], s[36:37], 0, v[130:131]
	s_mov_b32 m0, s19
	s_nop 0
	global_load_lds_dwordx4 v[246:247], off
	s_mov_b32 m0, s56
	s_nop 0
	global_load_lds_dwordx4 v[248:249], off
	s_waitcnt vmcnt(8)
	s_waitcnt lgkmcnt(0)
	s_barrier
; #define PG8_STAGE(bufoff, gbase, voff) do { _Pragma("unroll") for (int _i = 0; _i < 2; ++_i) \
;         __builtin_amdgcn_global_load_lds((const unsigned*)((const char*)(gbase) + (voff)[_i]), (LAS unsigned*)(lds + (bufoff) + ldsw + _i * 8192), 16, 0, 0); } while (0)
; #define PG8_LDA(dst, b, h) do { _Pragma("unroll") for (int m = 0; m < 4; ++m) _Pragma("unroll") for (int k = 0; k < 2; ++k) dst[m][k] = *(const LAS bf16x8*)(lds + PG8_SA(b, h) + aoff + m * 2048 + k * 1024); } while (0)
; #define PG8_LDB(dst, b, h) do { _Pragma("unroll") for (int n = 0; n < 2; ++n) _Pragma("unroll") for (int k = 0; k < 2; ++k) dst[n][k] = *(const LAS bf16x8*)(lds + PG8_SB(b, h) + boff + n * 2048 + k * 1024); } while (0)
; #define PG8_MMA(ai, bj, At, Bt) do { __builtin_amdgcn_s_setprio(1); _Pragma("unroll") for (int m = 0; m < 4; ++m) _Pragma("unroll") for (int n = 0; n < 2; ++n) _Pragma("unroll") for (int k = 0; k < 2; ++k) \
;         acc[ai][bj][m][n] = __builtin_amdgcn_mfma_f32_16x16x32_bf16(Bt[n][k], At[m][k], acc[ai][bj][m][n], 0, 0, 0); __builtin_amdgcn_s_setprio(0); } while (0)
; #define PG8_WAIT_V(n) asm volatile("s_waitcnt vmcnt(" #n ")" ::: "memory")
; #define PG8_WAIT_L(n) asm volatile("s_waitcnt lgkmcnt(" #n ")" ::: "memory")
; #define PG8_BAR __builtin_amdgcn_s_barrier()
; #define PG8_SCHED __builtin_amdgcn_sched_barrier(0)
; template <class Epi>
; __device__ __forceinline__ void gemm_phase(LAS unsigned char* lds, const Gemm g, const StaticOrder& S, const Epi& E) {
;     ...
;             PG8_WAIT_V(8); PG8_WAIT_L(0); PG8_BAR; PG8_MMA(1, 0, At, B0); PG8_MMA(1, 1, At, B1); PG8_BAR; PG8_SCHED;
;             PG8_LDB(B0, 1, 0); PG8_LDB(B1, 1, 1); PG8_SCHED; PG8_LDA(At, 1, 0); PG8_STAGE(PG8_SA(0, 1), a2 + hA, voffA);
;             PG8_WAIT_V(8); PG8_WAIT_L(0); PG8_BAR; PG8_MMA(0, 0, At, B0); PG8_MMA(0, 1, At, B1); PG8_BAR; PG8_SCHED;
	v_mfma_f32_16x16x32_bf16 v[62:65], v[166:169], v[202:205], v[62:65]
	v_mfma_f32_16x16x32_bf16 v[58:61], v[174:177], v[202:205], v[58:61]
	v_mfma_f32_16x16x32_bf16 v[46:49], v[166:169], v[210:213], v[46:49]
	v_mfma_f32_16x16x32_bf16 v[42:45], v[174:177], v[210:213], v[42:45]
	v_mfma_f32_16x16x32_bf16 v[30:33], v[166:169], v[218:221], v[30:33]
	v_mfma_f32_16x16x32_bf16 v[26:29], v[174:177], v[218:221], v[26:29]
	v_mfma_f32_16x16x32_bf16 v[14:17], v[166:169], v[236:239], v[14:17]
	v_mfma_f32_16x16x32_bf16 v[10:13], v[174:177], v[236:239], v[10:13]
	v_mfma_f32_16x16x32_bf16 v[62:65], v[170:173], v[206:209], v[62:65]
	v_mfma_f32_16x16x32_bf16 v[58:61], v[182:185], v[206:209], v[58:61]
	v_mfma_f32_16x16x32_bf16 v[46:49], v[170:173], v[214:217], v[46:49]
	v_mfma_f32_16x16x32_bf16 v[42:45], v[182:185], v[214:217], v[42:45]
	v_mfma_f32_16x16x32_bf16 v[30:33], v[170:173], v[232:235], v[30:33]
	v_mfma_f32_16x16x32_bf16 v[26:29], v[182:185], v[232:235], v[26:29]
	v_mfma_f32_16x16x32_bf16 v[14:17], v[170:173], v[240:243], v[14:17]
	v_mfma_f32_16x16x32_bf16 v[10:13], v[182:185], v[240:243], v[10:13]
	v_mfma_f32_16x16x32_bf16 v[54:57], v[186:189], v[202:205], v[54:57]
	v_mfma_f32_16x16x32_bf16 v[50:53], v[194:197], v[202:205], v[50:53]
	v_mfma_f32_16x16x32_bf16 v[38:41], v[186:189], v[210:213], v[38:41]
	v_mfma_f32_16x16x32_bf16 v[34:37], v[194:197], v[210:213], v[34:37]
	v_mfma_f32_16x16x32_bf16 v[22:25], v[186:189], v[218:221], v[22:25]
	v_mfma_f32_16x16x32_bf16 v[18:21], v[194:197], v[218:221], v[18:21]
	v_mfma_f32_16x16x32_bf16 v[6:9], v[186:189], v[236:239], v[6:9]
	v_mfma_f32_16x16x32_bf16 v[2:5], v[194:197], v[236:239], v[2:5]
	v_mfma_f32_16x16x32_bf16 v[54:57], v[190:193], v[206:209], v[54:57]
	v_mfma_f32_16x16x32_bf16 v[50:53], v[198:201], v[206:209], v[50:53]
	v_mfma_f32_16x16x32_bf16 v[38:41], v[190:193], v[214:217], v[38:41]
	v_mfma_f32_16x16x32_bf16 v[34:37], v[198:201], v[214:217], v[34:37]
	v_mfma_f32_16x16x32_bf16 v[22:25], v[190:193], v[232:235], v[22:25]
	v_mfma_f32_16x16x32_bf16 v[18:21], v[198:201], v[232:235], v[18:21]
	v_mfma_f32_16x16x32_bf16 v[6:9], v[190:193], v[240:243], v[6:9]
	v_mfma_f32_16x16x32_bf16 v[2:5], v[198:201], v[240:243], v[2:5]
	s_barrier
	s_add_i32 s42, 0, 0x18000
	v_add_u32_e32 v153, s42, v139
	s_add_i32 s43, 0, 0x1c000
	ds_read_b128 v[166:169], v153
	ds_read_b128 v[170:173], v153 offset:1024
	ds_read_b128 v[174:177], v153 offset:2048
	ds_read_b128 v[182:185], v153 offset:3072
	v_add_u32_e32 v153, s43, v139
	ds_read_b128 v[186:189], v153
	ds_read_b128 v[190:193], v153 offset:1024
	ds_read_b128 v[194:197], v153 offset:2048
	ds_read_b128 v[198:201], v153 offset:3072
	s_add_u32 s36, s36, 0x40000
	s_addc_u32 s37, s37, 0
	s_mov_b32 m0, s57
	v_lshl_add_u64 v[250:251], s[36:37], 0, v[130:131]
	ds_read_b128 v[202:205], v149 offset:32768
	ds_read_b128 v[206:209], v149 offset:33792
	ds_read_b128 v[210:213], v149 offset:34816
	ds_read_b128 v[214:217], v149 offset:35840
	ds_read_b128 v[218:221], v149 offset:36864
	ds_read_b128 v[232:235], v149 offset:37888
	ds_read_b128 v[236:239], v149 offset:38912
	ds_read_b128 v[240:243], v149 offset:39936
	global_load_lds_dwordx4 v[250:251], off
	v_lshl_add_u64 v[250:251], s[36:37], 0, v[134:135]
	s_mov_b32 m0, s58
	s_nop 0
	global_load_lds_dwordx4 v[250:251], off
	s_waitcnt vmcnt(8)
	s_waitcnt lgkmcnt(0)
	s_barrier
	v_mfma_f32_16x16x32_bf16 v[126:129], v[166:169], v[202:205], v[126:129]
	v_mfma_f32_16x16x32_bf16 v[122:125], v[174:177], v[202:205], v[122:125]
	v_mfma_f32_16x16x32_bf16 v[110:113], v[166:169], v[210:213], v[110:113]
	v_mfma_f32_16x16x32_bf16 v[106:109], v[174:177], v[210:213], v[106:109]
	v_mfma_f32_16x16x32_bf16 v[94:97], v[166:169], v[218:221], v[94:97]
	v_mfma_f32_16x16x32_bf16 v[90:93], v[174:177], v[218:221], v[90:93]
	v_mfma_f32_16x16x32_bf16 v[78:81], v[166:169], v[236:239], v[78:81]
	v_mfma_f32_16x16x32_bf16 v[74:77], v[174:177], v[236:239], v[74:77]
	v_mfma_f32_16x16x32_bf16 v[126:129], v[170:173], v[206:209], v[126:129]
	v_mfma_f32_16x16x32_bf16 v[122:125], v[182:185], v[206:209], v[122:125]
	v_mfma_f32_16x16x32_bf16 v[110:113], v[170:173], v[214:217], v[110:113]
	v_mfma_f32_16x16x32_bf16 v[106:109], v[182:185], v[214:217], v[106:109]
	v_mfma_f32_16x16x32_bf16 v[94:97], v[170:173], v[232:235], v[94:97]
	v_mfma_f32_16x16x32_bf16 v[90:93], v[182:185], v[232:235], v[90:93]
	v_mfma_f32_16x16x32_bf16 v[78:81], v[170:173], v[240:243], v[78:81]
	v_mfma_f32_16x16x32_bf16 v[74:77], v[182:185], v[240:243], v[74:77]
	v_mfma_f32_16x16x32_bf16 v[118:121], v[186:189], v[202:205], v[118:121]
	v_mfma_f32_16x16x32_bf16 v[114:117], v[194:197], v[202:205], v[114:117]
	v_mfma_f32_16x16x32_bf16 v[102:105], v[186:189], v[210:213], v[102:105]
	v_mfma_f32_16x16x32_bf16 v[98:101], v[194:197], v[210:213], v[98:101]
	v_mfma_f32_16x16x32_bf16 v[86:89], v[186:189], v[218:221], v[86:89]
	v_mfma_f32_16x16x32_bf16 v[82:85], v[194:197], v[218:221], v[82:85]
	v_mfma_f32_16x16x32_bf16 v[70:73], v[186:189], v[236:239], v[70:73]
	v_mfma_f32_16x16x32_bf16 v[66:69], v[194:197], v[236:239], v[66:69]
	v_mfma_f32_16x16x32_bf16 v[118:121], v[190:193], v[206:209], v[118:121]
	v_mfma_f32_16x16x32_bf16 v[114:117], v[198:201], v[206:209], v[114:117]
	v_mfma_f32_16x16x32_bf16 v[102:105], v[190:193], v[214:217], v[102:105]
	v_mfma_f32_16x16x32_bf16 v[98:101], v[198:201], v[214:217], v[98:101]
	v_mfma_f32_16x16x32_bf16 v[86:89], v[190:193], v[232:235], v[86:89]
	v_mfma_f32_16x16x32_bf16 v[82:85], v[198:201], v[232:235], v[82:85]
	v_mfma_f32_16x16x32_bf16 v[70:73], v[190:193], v[240:243], v[70:73]
	v_mfma_f32_16x16x32_bf16 v[66:69], v[198:201], v[240:243], v[66:69]
	s_barrier
; #define PG8_STAGE(bufoff, gbase, voff) do { _Pragma("unroll") for (int _i = 0; _i < 2; ++_i) \
;         __builtin_amdgcn_global_load_lds((const unsigned*)((const char*)(gbase) + (voff)[_i]), (LAS unsigned*)(lds + (bufoff) + ldsw + _i * 8192), 16, 0, 0); } while (0)
; #define PG8_LDA(dst, b, h) do { _Pragma("unroll") for (int m = 0; m < 4; ++m) _Pragma("unroll") for (int k = 0; k < 2; ++k) dst[m][k] = *(const LAS bf16x8*)(lds + PG8_SA(b, h) + aoff + m * 2048 + k * 1024); } while (0)
; #define PG8_MMA(ai, bj, At, Bt) do { __builtin_amdgcn_s_setprio(1); _Pragma("unroll") for (int m = 0; m < 4; ++m) _Pragma("unroll") for (int n = 0; n < 2; ++n) _Pragma("unroll") for (int k = 0; k < 2; ++k) \
;         acc[ai][bj][m][n] = __builtin_amdgcn_mfma_f32_16x16x32_bf16(Bt[n][k], At[m][k], acc[ai][bj][m][n], 0, 0, 0); __builtin_amdgcn_s_setprio(0); } while (0)
; #define PG8_WAIT_V(n) asm volatile("s_waitcnt vmcnt(" #n ")" ::: "memory")
; #define PG8_WAIT_L(n) asm volatile("s_waitcnt lgkmcnt(" #n ")" ::: "memory")
; #define PG8_BAR __builtin_amdgcn_s_barrier()
; #define PG8_SCHED __builtin_amdgcn_sched_barrier(0)
; template <class Epi>
; __device__ __forceinline__ void gemm_phase(LAS unsigned char* lds, const Gemm g, const StaticOrder& S, const Epi& E) {
;     ...
;             PG8_LDA(At, 1, 1); PG8_STAGE(PG8_SB(1, 0), b3, voffB); PG8_STAGE(PG8_SB(1, 1), b3 + hB, voffB); PG8_STAGE(PG8_SA(1, 0), a3, voffA);
;             PG8_WAIT_V(8); PG8_WAIT_L(0); PG8_BAR; PG8_MMA(1, 0, At, B0); PG8_MMA(1, 1, At, B1); PG8_BAR; PG8_SCHED;
;         }
;         if (wr == 0) PG8_BAR;
	s_add_i32 s36, s42, s51
	v_lshl_add_u64 v[178:179], v[178:179], 0, s[88:89]
	s_mov_b32 m0, s36
	ds_read_b128 v[202:205], v149 offset:49152
	ds_read_b128 v[206:209], v149 offset:50176
	ds_read_b128 v[210:213], v149 offset:51200
	ds_read_b128 v[214:217], v149 offset:52224
	ds_read_b128 v[218:221], v149 offset:53248
	ds_read_b128 v[232:235], v149 offset:54272
	ds_read_b128 v[236:239], v149 offset:55296
	ds_read_b128 v[240:243], v149 offset:56320
	global_load_lds_dwordx4 v[178:179], off
	s_add_i32 m0, s36, 0x2000
	s_add_u32 s34, s34, 0x40080
	v_lshl_add_u64 v[178:179], v[244:245], 0, s[88:89]
	s_addc_u32 s35, s35, 0
	s_add_i32 s36, s43, s51
	global_load_lds_dwordx4 v[178:179], off
	v_lshl_add_u64 v[178:179], s[34:35], 0, v[132:133]
	s_mov_b32 m0, s36
	s_nop 0
	global_load_lds_dwordx4 v[178:179], off
	v_lshl_add_u64 v[178:179], s[34:35], 0, v[136:137]
	s_add_i32 m0, s36, 0x2000
	s_nop 0
	global_load_lds_dwordx4 v[178:179], off
	v_lshl_add_u64 v[178:179], v[246:247], 0, s[88:89]
	s_mov_b32 m0, s60
	s_nop 0
	global_load_lds_dwordx4 v[178:179], off
	v_lshl_add_u64 v[178:179], v[248:249], 0, s[88:89]
	s_mov_b32 m0, s61
	s_nop 0
	global_load_lds_dwordx4 v[178:179], off
	s_waitcnt vmcnt(8)
	s_waitcnt lgkmcnt(0)
	s_barrier
	v_mfma_f32_16x16x32_bf16 v[62:65], v[166:169], v[202:205], v[62:65]
	v_mfma_f32_16x16x32_bf16 v[58:61], v[174:177], v[202:205], v[58:61]
	v_mfma_f32_16x16x32_bf16 v[46:49], v[166:169], v[210:213], v[46:49]
	v_mfma_f32_16x16x32_bf16 v[42:45], v[174:177], v[210:213], v[42:45]
	v_mfma_f32_16x16x32_bf16 v[30:33], v[166:169], v[218:221], v[30:33]
	v_mfma_f32_16x16x32_bf16 v[26:29], v[174:177], v[218:221], v[26:29]
	v_mfma_f32_16x16x32_bf16 v[14:17], v[166:169], v[236:239], v[14:17]
	v_mfma_f32_16x16x32_bf16 v[10:13], v[174:177], v[236:239], v[10:13]
	v_mfma_f32_16x16x32_bf16 v[62:65], v[170:173], v[206:209], v[62:65]
	v_mfma_f32_16x16x32_bf16 v[58:61], v[182:185], v[206:209], v[58:61]
	v_mfma_f32_16x16x32_bf16 v[46:49], v[170:173], v[214:217], v[46:49]
	v_mfma_f32_16x16x32_bf16 v[42:45], v[182:185], v[214:217], v[42:45]
	v_mfma_f32_16x16x32_bf16 v[30:33], v[170:173], v[232:235], v[30:33]
	v_mfma_f32_16x16x32_bf16 v[26:29], v[182:185], v[232:235], v[26:29]
	v_mfma_f32_16x16x32_bf16 v[14:17], v[170:173], v[240:243], v[14:17]
	v_mfma_f32_16x16x32_bf16 v[10:13], v[182:185], v[240:243], v[10:13]
	v_mfma_f32_16x16x32_bf16 v[54:57], v[186:189], v[202:205], v[54:57]
	v_mfma_f32_16x16x32_bf16 v[50:53], v[194:197], v[202:205], v[50:53]
	v_mfma_f32_16x16x32_bf16 v[38:41], v[186:189], v[210:213], v[38:41]
	v_mfma_f32_16x16x32_bf16 v[34:37], v[194:197], v[210:213], v[34:37]
	v_mfma_f32_16x16x32_bf16 v[22:25], v[186:189], v[218:221], v[22:25]
	v_mfma_f32_16x16x32_bf16 v[18:21], v[194:197], v[218:221], v[18:21]
	v_mfma_f32_16x16x32_bf16 v[6:9], v[186:189], v[236:239], v[6:9]
	v_mfma_f32_16x16x32_bf16 v[2:5], v[194:197], v[236:239], v[2:5]
	v_mfma_f32_16x16x32_bf16 v[54:57], v[190:193], v[206:209], v[54:57]
	v_mfma_f32_16x16x32_bf16 v[50:53], v[198:201], v[206:209], v[50:53]
	v_mfma_f32_16x16x32_bf16 v[38:41], v[190:193], v[214:217], v[38:41]
	v_mfma_f32_16x16x32_bf16 v[34:37], v[198:201], v[214:217], v[34:37]
	v_mfma_f32_16x16x32_bf16 v[22:25], v[190:193], v[232:235], v[22:25]
	v_mfma_f32_16x16x32_bf16 v[18:21], v[198:201], v[232:235], v[18:21]
	v_mfma_f32_16x16x32_bf16 v[6:9], v[190:193], v[240:243], v[6:9]
	v_mfma_f32_16x16x32_bf16 v[2:5], v[198:201], v[240:243], v[2:5]
	s_barrier
	s_add_i32 s41, s41, 2
	s_add_u32 s8, s8, 0x100
	s_addc_u32 s9, s9, 0
	s_add_u32 s39, s39, 0x100
	s_addc_u32 s40, s40, 0
	s_cmp_gt_u32 s41, 13
	s_cbranch_scc0 .LBB0_132
	s_and_b64 vcc, exec, s[16:17]
	s_cbranch_vccz .LBB0_135
	s_barrier

; #define PG8_STAGE(bufoff, gbase, voff) do { _Pragma("unroll") for (int _i = 0; _i < 2; ++_i) \
;         __builtin_amdgcn_global_load_lds((const unsigned*)((const char*)(gbase) + (voff)[_i]), (LAS unsigned*)(lds + (bufoff) + ldsw + _i * 8192), 16, 0, 0); } while (0)
; #define PG8_LDA(dst, b, h) do { _Pragma("unroll") for (int m = 0; m < 4; ++m) _Pragma("unroll") for (int k = 0; k < 2; ++k) dst[m][k] = *(const LAS bf16x8*)(lds + PG8_SA(b, h) + aoff + m * 2048 + k * 1024); } while (0)
; #define PG8_LDB(dst, b, h) do { _Pragma("unroll") for (int n = 0; n < 2; ++n) _Pragma("unroll") for (int k = 0; k < 2; ++k) dst[n][k] = *(const LAS bf16x8*)(lds + PG8_SB(b, h) + boff + n * 2048 + k * 1024); } while (0)
; #define PG8_MMA(ai, bj, At, Bt) do { __builtin_amdgcn_s_setprio(1); _Pragma("unroll") for (int m = 0; m < 4; ++m) _Pragma("unroll") for (int n = 0; n < 2; ++n) _Pragma("unroll") for (int k = 0; k < 2; ++k) \
;         acc[ai][bj][m][n] = __builtin_amdgcn_mfma_f32_16x16x32_bf16(Bt[n][k], At[m][k], acc[ai][bj][m][n], 0, 0, 0); __builtin_amdgcn_s_setprio(0); } while (0)
; #define PG8_WAIT_V(n) asm volatile("s_waitcnt vmcnt(" #n ")" ::: "memory")
; #define PG8_WAIT_L(n) asm volatile("s_waitcnt lgkmcnt(" #n ")" ::: "memory")
; #define PG8_BAR __builtin_amdgcn_s_barrier()
; #define PG8_SCHED __builtin_amdgcn_sched_barrier(0)
; template <class Epi>
; __device__ __forceinline__ void gemm_phase(LAS unsigned char* lds, const Gemm g, const StaticOrder& S, const Epi& E) {
;     ...
;             PG8_LDB(B0, 0, 0); PG8_LDB(B1, 0, 1); PG8_SCHED; PG8_LDA(At, 0, 0); PG8_STAGE(PG8_SA(1, 1), a1 + hA, voffA);
;             PG8_WAIT_V(8); PG8_WAIT_L(0); PG8_BAR; PG8_MMA(0, 0, At, B0); PG8_MMA(0, 1, At, B1); PG8_BAR; PG8_SCHED;
;             PG8_LDA(At, 0, 1); PG8_STAGE(PG8_SB(0, 0), b2, voffB); PG8_STAGE(PG8_SB(0, 1), b2 + hB, voffB); PG8_STAGE(PG8_SA(0, 0), a2, voffA);
;             PG8_WAIT_V(8); PG8_WAIT_L(0); PG8_BAR; PG8_MMA(1, 0, At, B0); PG8_MMA(1, 1, At, B1); PG8_BAR; PG8_SCHED;
.LBB0_518:
	s_add_u32 s30, s28, 0xfffc0080
	s_addc_u32 s31, s29, -1
	s_add_i32 s71, 0, 0x10000
	s_cmp_eq_u32 s70, 28
	s_cselect_b32 s35, s21, s31
	s_cselect_b32 s34, s27, s30
	v_add_u32_e32 v154, s71, v156
	s_cselect_b32 s31, s19, s67
	s_cselect_b32 s30, s65, s66
	s_add_i32 s73, 0, 0x14000
	ds_read_b128 v[98:101], v154
	ds_read_b128 v[102:105], v154 offset:1024
	ds_read_b128 v[158:161], v154 offset:2048
	ds_read_b128 v[162:165], v154 offset:3072
	v_add_u32_e32 v154, s73, v156
	ds_read_b128 v[166:169], v154
	ds_read_b128 v[170:173], v154 offset:1024
	ds_read_b128 v[174:177], v154 offset:2048
	ds_read_b128 v[182:185], v154 offset:3072
	v_lshl_add_u64 v[154:155], s[28:29], 0, v[150:151]
	s_add_i32 m0, s54, 0xc000
	ds_read_b128 v[186:189], v157
	ds_read_b128 v[190:193], v157 offset:1024
	ds_read_b128 v[194:197], v157 offset:2048
	ds_read_b128 v[198:201], v157 offset:3072
	ds_read_b128 v[202:205], v157 offset:4096
	ds_read_b128 v[206:209], v157 offset:5120
	ds_read_b128 v[210:213], v157 offset:6144
	ds_read_b128 v[214:217], v157 offset:7168
	global_load_lds_dwordx4 v[154:155], off
	v_lshl_add_u64 v[154:155], s[28:29], 0, v[152:153]
	s_add_i32 m0, s54, 0xe000
	s_nop 0
	global_load_lds_dwordx4 v[154:155], off
	s_waitcnt vmcnt(8)
	s_waitcnt lgkmcnt(0)
	s_barrier
	v_mfma_f32_16x16x32_bf16 v[134:137], v[98:101], v[186:189], v[134:137]
	v_mfma_f32_16x16x32_bf16 v[130:133], v[158:161], v[186:189], v[130:133]
	v_mfma_f32_16x16x32_bf16 v[126:129], v[98:101], v[194:197], v[126:129]
	v_mfma_f32_16x16x32_bf16 v[122:125], v[158:161], v[194:197], v[122:125]
	v_mfma_f32_16x16x32_bf16 v[118:121], v[98:101], v[202:205], v[118:121]
	v_mfma_f32_16x16x32_bf16 v[114:117], v[158:161], v[202:205], v[114:117]
	v_mfma_f32_16x16x32_bf16 v[110:113], v[98:101], v[210:213], v[110:113]
	v_mfma_f32_16x16x32_bf16 v[106:109], v[158:161], v[210:213], v[106:109]
	v_mfma_f32_16x16x32_bf16 v[134:137], v[102:105], v[190:193], v[134:137]
	v_mfma_f32_16x16x32_bf16 v[130:133], v[162:165], v[190:193], v[130:133]
	v_mfma_f32_16x16x32_bf16 v[126:129], v[102:105], v[198:201], v[126:129]
	v_mfma_f32_16x16x32_bf16 v[122:125], v[162:165], v[198:201], v[122:125]
	v_mfma_f32_16x16x32_bf16 v[118:121], v[102:105], v[206:209], v[118:121]
	v_mfma_f32_16x16x32_bf16 v[114:117], v[162:165], v[206:209], v[114:117]
	v_mfma_f32_16x16x32_bf16 v[110:113], v[102:105], v[214:217], v[110:113]
	v_mfma_f32_16x16x32_bf16 v[106:109], v[162:165], v[214:217], v[106:109]
	v_mfma_f32_16x16x32_bf16 v[62:65], v[166:169], v[186:189], v[62:65]
	v_mfma_f32_16x16x32_bf16 v[58:61], v[174:177], v[186:189], v[58:61]
	v_mfma_f32_16x16x32_bf16 v[54:57], v[166:169], v[194:197], v[54:57]
	v_mfma_f32_16x16x32_bf16 v[50:53], v[174:177], v[194:197], v[50:53]
	v_mfma_f32_16x16x32_bf16 v[46:49], v[166:169], v[202:205], v[46:49]
	v_mfma_f32_16x16x32_bf16 v[42:45], v[174:177], v[202:205], v[42:45]
	v_mfma_f32_16x16x32_bf16 v[38:41], v[166:169], v[210:213], v[38:41]
	v_mfma_f32_16x16x32_bf16 v[34:37], v[174:177], v[210:213], v[34:37]
	v_mfma_f32_16x16x32_bf16 v[62:65], v[170:173], v[190:193], v[62:65]
	v_mfma_f32_16x16x32_bf16 v[58:61], v[182:185], v[190:193], v[58:61]
	v_mfma_f32_16x16x32_bf16 v[54:57], v[170:173], v[198:201], v[54:57]
	v_mfma_f32_16x16x32_bf16 v[50:53], v[182:185], v[198:201], v[50:53]
	v_mfma_f32_16x16x32_bf16 v[46:49], v[170:173], v[206:209], v[46:49]
	v_mfma_f32_16x16x32_bf16 v[42:45], v[182:185], v[206:209], v[42:45]
	v_mfma_f32_16x16x32_bf16 v[38:41], v[170:173], v[214:217], v[38:41]
	v_mfma_f32_16x16x32_bf16 v[34:37], v[182:185], v[214:217], v[34:37]
	s_barrier
	s_add_i32 s71, s71, s53
	v_lshl_add_u64 v[154:155], s[30:31], 0, v[140:141]
	s_mov_b32 m0, s71
	ds_read_b128 v[186:189], v157 offset:16384
	ds_read_b128 v[190:193], v157 offset:17408
	ds_read_b128 v[194:197], v157 offset:18432
	ds_read_b128 v[198:201], v157 offset:19456
	ds_read_b128 v[202:205], v157 offset:20480
	ds_read_b128 v[206:209], v157 offset:21504
	ds_read_b128 v[210:213], v157 offset:22528
	ds_read_b128 v[214:217], v157 offset:23552
	global_load_lds_dwordx4 v[154:155], off
	s_add_i32 m0, s71, 0x2000
	s_add_u32 s74, s30, 0x80000
	v_lshl_add_u64 v[178:179], s[30:31], 0, v[144:145]
	s_addc_u32 s75, s31, 0
	s_add_i32 s71, s73, s53
	global_load_lds_dwordx4 v[178:179], off
	v_lshl_add_u64 v[218:219], s[74:75], 0, v[140:141]
	s_mov_b32 m0, s71
	v_lshl_add_u64 v[220:221], s[34:35], 0, v[142:143]
	global_load_lds_dwordx4 v[218:219], off
	v_lshl_add_u64 v[218:219], s[74:75], 0, v[144:145]
	s_add_i32 m0, s71, 0x2000
	s_nop 0
	global_load_lds_dwordx4 v[218:219], off
	v_lshl_add_u64 v[218:219], s[34:35], 0, v[138:139]
	s_mov_b32 m0, s54
	s_nop 0
	global_load_lds_dwordx4 v[218:219], off
	s_mov_b32 m0, s55
	s_nop 0
	global_load_lds_dwordx4 v[220:221], off
	s_waitcnt vmcnt(8)
	s_waitcnt lgkmcnt(0)
	s_barrier
; #define PG8_STAGE(bufoff, gbase, voff) do { _Pragma("unroll") for (int _i = 0; _i < 2; ++_i) \
;         __builtin_amdgcn_global_load_lds((const unsigned*)((const char*)(gbase) + (voff)[_i]), (LAS unsigned*)(lds + (bufoff) + ldsw + _i * 8192), 16, 0, 0); } while (0)
; #define PG8_LDA(dst, b, h) do { _Pragma("unroll") for (int m = 0; m < 4; ++m) _Pragma("unroll") for (int k = 0; k < 2; ++k) dst[m][k] = *(const LAS bf16x8*)(lds + PG8_SA(b, h) + aoff + m * 2048 + k * 1024); } while (0)
; #define PG8_LDB(dst, b, h) do { _Pragma("unroll") for (int n = 0; n < 2; ++n) _Pragma("unroll") for (int k = 0; k < 2; ++k) dst[n][k] = *(const LAS bf16x8*)(lds + PG8_SB(b, h) + boff + n * 2048 + k * 1024); } while (0)
; #define PG8_MMA(ai, bj, At, Bt) do { __builtin_amdgcn_s_setprio(1); _Pragma("unroll") for (int m = 0; m < 4; ++m) _Pragma("unroll") for (int n = 0; n < 2; ++n) _Pragma("unroll") for (int k = 0; k < 2; ++k) \
;         acc[ai][bj][m][n] = __builtin_amdgcn_mfma_f32_16x16x32_bf16(Bt[n][k], At[m][k], acc[ai][bj][m][n], 0, 0, 0); __builtin_amdgcn_s_setprio(0); } while (0)
; #define PG8_WAIT_V(n) asm volatile("s_waitcnt vmcnt(" #n ")" ::: "memory")
; #define PG8_WAIT_L(n) asm volatile("s_waitcnt lgkmcnt(" #n ")" ::: "memory")
; #define PG8_BAR __builtin_amdgcn_s_barrier()
; #define PG8_SCHED __builtin_amdgcn_sched_barrier(0)
; template <class Epi>
; __device__ __forceinline__ void gemm_phase(LAS unsigned char* lds, const Gemm g, const StaticOrder& S, const Epi& E) {
;     ...
;             PG8_WAIT_V(8); PG8_WAIT_L(0); PG8_BAR; PG8_MMA(0, 0, At, B0); PG8_MMA(0, 1, At, B1); PG8_BAR; PG8_SCHED;
;             PG8_LDA(At, 0, 1); PG8_STAGE(PG8_SB(0, 0), b2, voffB); PG8_STAGE(PG8_SB(0, 1), b2 + hB, voffB); PG8_STAGE(PG8_SA(0, 0), a2, voffA);
;             PG8_WAIT_V(8); PG8_WAIT_L(0); PG8_BAR; PG8_MMA(1, 0, At, B0); PG8_MMA(1, 1, At, B1); PG8_BAR; PG8_SCHED;
;             PG8_LDB(B0, 1, 0); PG8_LDB(B1, 1, 1); PG8_SCHED; PG8_LDA(At, 1, 0); PG8_STAGE(PG8_SA(0, 1), a2 + hA, voffA);
;             PG8_WAIT_V(8); PG8_WAIT_L(0); PG8_BAR; PG8_MMA(0, 0, At, B0); PG8_MMA(0, 1, At, B1); PG8_BAR; PG8_SCHED;
	v_mfma_f32_16x16x32_bf16 v[94:97], v[98:101], v[186:189], v[94:97]
	v_mfma_f32_16x16x32_bf16 v[90:93], v[158:161], v[186:189], v[90:93]
	v_mfma_f32_16x16x32_bf16 v[86:89], v[98:101], v[194:197], v[86:89]
	v_mfma_f32_16x16x32_bf16 v[82:85], v[158:161], v[194:197], v[82:85]
	v_mfma_f32_16x16x32_bf16 v[78:81], v[98:101], v[202:205], v[78:81]
	v_mfma_f32_16x16x32_bf16 v[74:77], v[158:161], v[202:205], v[74:77]
	v_mfma_f32_16x16x32_bf16 v[70:73], v[98:101], v[210:213], v[70:73]
	v_mfma_f32_16x16x32_bf16 v[66:69], v[158:161], v[210:213], v[66:69]
	v_mfma_f32_16x16x32_bf16 v[94:97], v[102:105], v[190:193], v[94:97]
	v_mfma_f32_16x16x32_bf16 v[90:93], v[162:165], v[190:193], v[90:93]
	v_mfma_f32_16x16x32_bf16 v[86:89], v[102:105], v[198:201], v[86:89]
	v_mfma_f32_16x16x32_bf16 v[82:85], v[162:165], v[198:201], v[82:85]
	v_mfma_f32_16x16x32_bf16 v[78:81], v[102:105], v[206:209], v[78:81]
	v_mfma_f32_16x16x32_bf16 v[74:77], v[162:165], v[206:209], v[74:77]
	v_mfma_f32_16x16x32_bf16 v[70:73], v[102:105], v[214:217], v[70:73]
	v_mfma_f32_16x16x32_bf16 v[66:69], v[162:165], v[214:217], v[66:69]
	v_mfma_f32_16x16x32_bf16 v[30:33], v[166:169], v[186:189], v[30:33]
	v_mfma_f32_16x16x32_bf16 v[26:29], v[174:177], v[186:189], v[26:29]
	v_mfma_f32_16x16x32_bf16 v[22:25], v[166:169], v[194:197], v[22:25]
	v_mfma_f32_16x16x32_bf16 v[18:21], v[174:177], v[194:197], v[18:21]
	v_mfma_f32_16x16x32_bf16 v[14:17], v[166:169], v[202:205], v[14:17]
	v_mfma_f32_16x16x32_bf16 v[10:13], v[174:177], v[202:205], v[10:13]
	v_mfma_f32_16x16x32_bf16 v[6:9], v[166:169], v[210:213], v[6:9]
	v_mfma_f32_16x16x32_bf16 v[2:5], v[174:177], v[210:213], v[2:5]
	v_mfma_f32_16x16x32_bf16 v[30:33], v[170:173], v[190:193], v[30:33]
	v_mfma_f32_16x16x32_bf16 v[26:29], v[182:185], v[190:193], v[26:29]
	v_mfma_f32_16x16x32_bf16 v[22:25], v[170:173], v[198:201], v[22:25]
	v_mfma_f32_16x16x32_bf16 v[18:21], v[182:185], v[198:201], v[18:21]
	v_mfma_f32_16x16x32_bf16 v[14:17], v[170:173], v[206:209], v[14:17]
	v_mfma_f32_16x16x32_bf16 v[10:13], v[182:185], v[206:209], v[10:13]
	v_mfma_f32_16x16x32_bf16 v[6:9], v[170:173], v[214:217], v[6:9]
	v_mfma_f32_16x16x32_bf16 v[2:5], v[182:185], v[214:217], v[2:5]
	s_barrier
	s_add_i32 s71, 0, 0x18000
	s_add_i32 s73, 0, 0x1c000
	v_add_u32_e32 v162, s71, v156
	v_add_u32_e32 v180, s73, v156
	ds_read_b128 v[98:101], v162
	ds_read_b128 v[102:105], v162 offset:1024
	ds_read_b128 v[158:161], v162 offset:2048
	ds_read_b128 v[162:165], v162 offset:3072
	ds_read_b128 v[166:169], v180
	ds_read_b128 v[170:173], v180 offset:1024
	ds_read_b128 v[174:177], v180 offset:2048
	ds_read_b128 v[182:185], v180 offset:3072
	s_add_u32 s34, s34, 0x40000
	s_addc_u32 s35, s35, 0
	s_mov_b32 m0, s56
	v_lshl_add_u64 v[232:233], s[34:35], 0, v[138:139]
	ds_read_b128 v[186:189], v157 offset:32768
	ds_read_b128 v[190:193], v157 offset:33792
	ds_read_b128 v[194:197], v157 offset:34816
	ds_read_b128 v[198:201], v157 offset:35840
	ds_read_b128 v[202:205], v157 offset:36864
	ds_read_b128 v[206:209], v157 offset:37888
	ds_read_b128 v[210:213], v157 offset:38912
	ds_read_b128 v[214:217], v157 offset:39936
	global_load_lds_dwordx4 v[232:233], off
	v_lshl_add_u64 v[232:233], s[34:35], 0, v[142:143]
	s_mov_b32 m0, s57
	s_nop 0
	global_load_lds_dwordx4 v[232:233], off
	s_waitcnt vmcnt(8)
	s_waitcnt lgkmcnt(0)
	s_barrier
	v_mfma_f32_16x16x32_bf16 v[134:137], v[98:101], v[186:189], v[134:137]
	v_mfma_f32_16x16x32_bf16 v[130:133], v[158:161], v[186:189], v[130:133]
	v_mfma_f32_16x16x32_bf16 v[126:129], v[98:101], v[194:197], v[126:129]
	v_mfma_f32_16x16x32_bf16 v[122:125], v[158:161], v[194:197], v[122:125]
	v_mfma_f32_16x16x32_bf16 v[118:121], v[98:101], v[202:205], v[118:121]
	v_mfma_f32_16x16x32_bf16 v[114:117], v[158:161], v[202:205], v[114:117]
	v_mfma_f32_16x16x32_bf16 v[110:113], v[98:101], v[210:213], v[110:113]
	v_mfma_f32_16x16x32_bf16 v[106:109], v[158:161], v[210:213], v[106:109]
	v_mfma_f32_16x16x32_bf16 v[134:137], v[102:105], v[190:193], v[134:137]
	v_mfma_f32_16x16x32_bf16 v[130:133], v[162:165], v[190:193], v[130:133]
	v_mfma_f32_16x16x32_bf16 v[126:129], v[102:105], v[198:201], v[126:129]
	v_mfma_f32_16x16x32_bf16 v[122:125], v[162:165], v[198:201], v[122:125]
	v_mfma_f32_16x16x32_bf16 v[118:121], v[102:105], v[206:209], v[118:121]
	v_mfma_f32_16x16x32_bf16 v[114:117], v[162:165], v[206:209], v[114:117]
	v_mfma_f32_16x16x32_bf16 v[110:113], v[102:105], v[214:217], v[110:113]
	v_mfma_f32_16x16x32_bf16 v[106:109], v[162:165], v[214:217], v[106:109]
	v_mfma_f32_16x16x32_bf16 v[62:65], v[166:169], v[186:189], v[62:65]
	v_mfma_f32_16x16x32_bf16 v[58:61], v[174:177], v[186:189], v[58:61]
	v_mfma_f32_16x16x32_bf16 v[54:57], v[166:169], v[194:197], v[54:57]
	v_mfma_f32_16x16x32_bf16 v[50:53], v[174:177], v[194:197], v[50:53]
	v_mfma_f32_16x16x32_bf16 v[46:49], v[166:169], v[202:205], v[46:49]
	v_mfma_f32_16x16x32_bf16 v[42:45], v[174:177], v[202:205], v[42:45]
	v_mfma_f32_16x16x32_bf16 v[38:41], v[166:169], v[210:213], v[38:41]
	v_mfma_f32_16x16x32_bf16 v[34:37], v[174:177], v[210:213], v[34:37]
	v_mfma_f32_16x16x32_bf16 v[62:65], v[170:173], v[190:193], v[62:65]
	v_mfma_f32_16x16x32_bf16 v[58:61], v[182:185], v[190:193], v[58:61]
	v_mfma_f32_16x16x32_bf16 v[54:57], v[170:173], v[198:201], v[54:57]
	v_mfma_f32_16x16x32_bf16 v[50:53], v[182:185], v[198:201], v[50:53]
	v_mfma_f32_16x16x32_bf16 v[46:49], v[170:173], v[206:209], v[46:49]
	v_mfma_f32_16x16x32_bf16 v[42:45], v[182:185], v[206:209], v[42:45]
	v_mfma_f32_16x16x32_bf16 v[38:41], v[170:173], v[214:217], v[38:41]
	v_mfma_f32_16x16x32_bf16 v[34:37], v[182:185], v[214:217], v[34:37]
	s_barrier
; #define PG8_STAGE(bufoff, gbase, voff) do { _Pragma("unroll") for (int _i = 0; _i < 2; ++_i) \
;         __builtin_amdgcn_global_load_lds((const unsigned*)((const char*)(gbase) + (voff)[_i]), (LAS unsigned*)(lds + (bufoff) + ldsw + _i * 8192), 16, 0, 0); } while (0)
; #define PG8_LDA(dst, b, h) do { _Pragma("unroll") for (int m = 0; m < 4; ++m) _Pragma("unroll") for (int k = 0; k < 2; ++k) dst[m][k] = *(const LAS bf16x8*)(lds + PG8_SA(b, h) + aoff + m * 2048 + k * 1024); } while (0)
; #define PG8_MMA(ai, bj, At, Bt) do { __builtin_amdgcn_s_setprio(1); _Pragma("unroll") for (int m = 0; m < 4; ++m) _Pragma("unroll") for (int n = 0; n < 2; ++n) _Pragma("unroll") for (int k = 0; k < 2; ++k) \
;         acc[ai][bj][m][n] = __builtin_amdgcn_mfma_f32_16x16x32_bf16(Bt[n][k], At[m][k], acc[ai][bj][m][n], 0, 0, 0); __builtin_amdgcn_s_setprio(0); } while (0)
; #define PG8_WAIT_V(n) asm volatile("s_waitcnt vmcnt(" #n ")" ::: "memory")
; #define PG8_WAIT_L(n) asm volatile("s_waitcnt lgkmcnt(" #n ")" ::: "memory")
; #define PG8_BAR __builtin_amdgcn_s_barrier()
; #define PG8_SCHED __builtin_amdgcn_sched_barrier(0)
; template <class Epi>
; __device__ __forceinline__ void gemm_phase(LAS unsigned char* lds, const Gemm g, const StaticOrder& S, const Epi& E) {
;     ...
;             PG8_LDA(At, 1, 1); PG8_STAGE(PG8_SB(1, 0), b3, voffB); PG8_STAGE(PG8_SB(1, 1), b3 + hB, voffB); PG8_STAGE(PG8_SA(1, 0), a3, voffA);
;             PG8_WAIT_V(8); PG8_WAIT_L(0); PG8_BAR; PG8_MMA(1, 0, At, B0); PG8_MMA(1, 1, At, B1); PG8_BAR; PG8_SCHED;
;         }
;         if (wr == 0) PG8_BAR;
	s_add_i32 s34, s71, s53
	v_lshl_add_u64 v[154:155], v[154:155], 0, s[88:89]
	s_mov_b32 m0, s34
	ds_read_b128 v[186:189], v157 offset:49152
	ds_read_b128 v[190:193], v157 offset:50176
	ds_read_b128 v[194:197], v157 offset:51200
	ds_read_b128 v[198:201], v157 offset:52224
	ds_read_b128 v[202:205], v157 offset:53248
	ds_read_b128 v[206:209], v157 offset:54272
	ds_read_b128 v[210:213], v157 offset:55296
	ds_read_b128 v[214:217], v157 offset:56320
	global_load_lds_dwordx4 v[154:155], off
	s_add_i32 m0, s34, 0x2000
	s_add_u32 s30, s30, 0x80080
	v_lshl_add_u64 v[154:155], v[178:179], 0, s[88:89]
	s_addc_u32 s31, s31, 0
	s_add_i32 s34, s73, s53
	global_load_lds_dwordx4 v[154:155], off
	v_lshl_add_u64 v[154:155], s[30:31], 0, v[140:141]
	s_mov_b32 m0, s34
	s_nop 0
	global_load_lds_dwordx4 v[154:155], off
	v_lshl_add_u64 v[154:155], s[30:31], 0, v[144:145]
	s_add_i32 m0, s34, 0x2000
	s_nop 0
	global_load_lds_dwordx4 v[154:155], off
	v_lshl_add_u64 v[154:155], v[218:219], 0, s[88:89]
	s_mov_b32 m0, s59
	s_nop 0
	global_load_lds_dwordx4 v[154:155], off
	v_lshl_add_u64 v[154:155], v[220:221], 0, s[88:89]
	s_mov_b32 m0, s60
	s_nop 0
	global_load_lds_dwordx4 v[154:155], off
	s_waitcnt vmcnt(8)
	s_waitcnt lgkmcnt(0)
	s_barrier
	v_mfma_f32_16x16x32_bf16 v[94:97], v[98:101], v[186:189], v[94:97]
	v_mfma_f32_16x16x32_bf16 v[90:93], v[158:161], v[186:189], v[90:93]
	v_mfma_f32_16x16x32_bf16 v[86:89], v[98:101], v[194:197], v[86:89]
	v_mfma_f32_16x16x32_bf16 v[82:85], v[158:161], v[194:197], v[82:85]
	v_mfma_f32_16x16x32_bf16 v[78:81], v[98:101], v[202:205], v[78:81]
	v_mfma_f32_16x16x32_bf16 v[74:77], v[158:161], v[202:205], v[74:77]
	v_mfma_f32_16x16x32_bf16 v[70:73], v[98:101], v[210:213], v[70:73]
	v_mfma_f32_16x16x32_bf16 v[66:69], v[158:161], v[210:213], v[66:69]
	v_mfma_f32_16x16x32_bf16 v[94:97], v[102:105], v[190:193], v[94:97]
	v_mfma_f32_16x16x32_bf16 v[90:93], v[162:165], v[190:193], v[90:93]
	v_mfma_f32_16x16x32_bf16 v[86:89], v[102:105], v[198:201], v[86:89]
	v_mfma_f32_16x16x32_bf16 v[82:85], v[162:165], v[198:201], v[82:85]
	v_mfma_f32_16x16x32_bf16 v[78:81], v[102:105], v[206:209], v[78:81]
	v_mfma_f32_16x16x32_bf16 v[74:77], v[162:165], v[206:209], v[74:77]
	v_mfma_f32_16x16x32_bf16 v[70:73], v[102:105], v[214:217], v[70:73]
	v_mfma_f32_16x16x32_bf16 v[66:69], v[162:165], v[214:217], v[66:69]
	v_mfma_f32_16x16x32_bf16 v[30:33], v[166:169], v[186:189], v[30:33]
	v_mfma_f32_16x16x32_bf16 v[26:29], v[174:177], v[186:189], v[26:29]
	v_mfma_f32_16x16x32_bf16 v[22:25], v[166:169], v[194:197], v[22:25]
	v_mfma_f32_16x16x32_bf16 v[18:21], v[174:177], v[194:197], v[18:21]
	v_mfma_f32_16x16x32_bf16 v[14:17], v[166:169], v[202:205], v[14:17]
	v_mfma_f32_16x16x32_bf16 v[10:13], v[174:177], v[202:205], v[10:13]
	v_mfma_f32_16x16x32_bf16 v[6:9], v[166:169], v[210:213], v[6:9]
	v_mfma_f32_16x16x32_bf16 v[2:5], v[174:177], v[210:213], v[2:5]
	v_mfma_f32_16x16x32_bf16 v[30:33], v[170:173], v[190:193], v[30:33]
	v_mfma_f32_16x16x32_bf16 v[26:29], v[182:185], v[190:193], v[26:29]
	v_mfma_f32_16x16x32_bf16 v[22:25], v[170:173], v[198:201], v[22:25]
	v_mfma_f32_16x16x32_bf16 v[18:21], v[182:185], v[198:201], v[18:21]
	v_mfma_f32_16x16x32_bf16 v[14:17], v[170:173], v[206:209], v[14:17]
	v_mfma_f32_16x16x32_bf16 v[10:13], v[182:185], v[206:209], v[10:13]
	v_mfma_f32_16x16x32_bf16 v[6:9], v[170:173], v[214:217], v[6:9]
	v_mfma_f32_16x16x32_bf16 v[2:5], v[182:185], v[214:217], v[2:5]
	s_barrier
	s_add_i32 s70, s70, 2
	s_add_u32 s28, s28, 0x100
	s_addc_u32 s29, s29, 0
	s_add_u32 s66, s66, 0x100
	s_addc_u32 s67, s67, 0
	s_cmp_gt_u32 s70, 29
	s_cbranch_scc0 .LBB0_518
	s_and_b64 vcc, exec, s[16:17]
	s_cbranch_vccz .LBB0_521
	s_barrier

; #define PG8_STAGE(bufoff, gbase, voff) do { _Pragma("unroll") for (int _i = 0; _i < 2; ++_i) \
;         __builtin_amdgcn_global_load_lds((const unsigned*)((const char*)(gbase) + (voff)[_i]), (LAS unsigned*)(lds + (bufoff) + ldsw + _i * 8192), 16, 0, 0); } while (0)
; #define PG8_LDA(dst, b, h) do { _Pragma("unroll") for (int m = 0; m < 4; ++m) _Pragma("unroll") for (int k = 0; k < 2; ++k) dst[m][k] = *(const LAS bf16x8*)(lds + PG8_SA(b, h) + aoff + m * 2048 + k * 1024); } while (0)
; #define PG8_LDB(dst, b, h) do { _Pragma("unroll") for (int n = 0; n < 2; ++n) _Pragma("unroll") for (int k = 0; k < 2; ++k) dst[n][k] = *(const LAS bf16x8*)(lds + PG8_SB(b, h) + boff + n * 2048 + k * 1024); } while (0)
; #define PG8_MMA(ai, bj, At, Bt) do { __builtin_amdgcn_s_setprio(1); _Pragma("unroll") for (int m = 0; m < 4; ++m) _Pragma("unroll") for (int n = 0; n < 2; ++n) _Pragma("unroll") for (int k = 0; k < 2; ++k) \
;         acc[ai][bj][m][n] = __builtin_amdgcn_mfma_f32_16x16x32_bf16(Bt[n][k], At[m][k], acc[ai][bj][m][n], 0, 0, 0); __builtin_amdgcn_s_setprio(0); } while (0)
; #define PG8_WAIT_V(n) asm volatile("s_waitcnt vmcnt(" #n ")" ::: "memory")
; #define PG8_WAIT_L(n) asm volatile("s_waitcnt lgkmcnt(" #n ")" ::: "memory")
; #define PG8_BAR __builtin_amdgcn_s_barrier()
; #define PG8_SCHED __builtin_amdgcn_sched_barrier(0)
; template <class Epi>
; __device__ __forceinline__ void gemm_phase(LAS unsigned char* lds, const Gemm g, const StaticOrder& S, const Epi& E) {
;     ...
;             PG8_LDB(B0, 0, 0); PG8_LDB(B1, 0, 1); PG8_SCHED; PG8_LDA(At, 0, 0); PG8_STAGE(PG8_SA(1, 1), a1 + hA, voffA);
;             PG8_WAIT_V(8); PG8_WAIT_L(0); PG8_BAR; PG8_MMA(0, 0, At, B0); PG8_MMA(0, 1, At, B1); PG8_BAR; PG8_SCHED;
;             PG8_LDA(At, 0, 1); PG8_STAGE(PG8_SB(0, 0), b2, voffB); PG8_STAGE(PG8_SB(0, 1), b2 + hB, voffB); PG8_STAGE(PG8_SA(0, 0), a2, voffA);
;             PG8_WAIT_V(8); PG8_WAIT_L(0); PG8_BAR; PG8_MMA(1, 0, At, B0); PG8_MMA(1, 1, At, B1); PG8_BAR; PG8_SCHED;
.LBB0_1398:
	s_add_u32 s10, s8, 0xfffc0080
	s_addc_u32 s11, s9, -1
	s_add_i32 s35, 0, 0x10000
	s_cmp_eq_u32 s31, 12
	s_cselect_b32 s41, s37, s11
	s_cselect_b32 s40, s36, s10
	s_cselect_b32 s11, s39, s29
	s_cselect_b32 s10, s38, s27
	s_add_i32 s64, 0, 0x14000
	v_add_u32_e32 v158, s35, v180
	v_add_u32_e32 v174, s64, v180
	ds_read_b128 v[146:149], v158
	ds_read_b128 v[150:153], v158 offset:1024
	ds_read_b128 v[154:157], v158 offset:2048
	ds_read_b128 v[158:161], v158 offset:3072
	ds_read_b128 v[162:165], v174
	ds_read_b128 v[166:169], v174 offset:1024
	ds_read_b128 v[170:173], v174 offset:2048
	ds_read_b128 v[174:177], v174 offset:3072
	v_lshl_add_u64 v[178:179], s[8:9], 0, v[142:143]
	s_add_i32 m0, s51, 0xc000
	ds_read_b128 v[182:185], v211
	ds_read_b128 v[186:189], v211 offset:1024
	ds_read_b128 v[190:193], v211 offset:2048
	ds_read_b128 v[194:197], v211 offset:3072
	ds_read_b128 v[198:201], v211 offset:4096
	ds_read_b128 v[202:205], v211 offset:5120
	ds_read_b128 v[216:219], v211 offset:6144
	ds_read_b128 v[232:235], v211 offset:7168
	global_load_lds_dwordx4 v[178:179], off
	v_lshl_add_u64 v[178:179], s[8:9], 0, v[144:145]
	s_add_i32 m0, s51, 0xe000
	s_nop 0
	global_load_lds_dwordx4 v[178:179], off
	s_waitcnt vmcnt(8)
	s_waitcnt lgkmcnt(0)
	s_barrier
	v_mfma_f32_16x16x32_bf16 v[126:129], v[146:149], v[182:185], v[126:129]
	v_mfma_f32_16x16x32_bf16 v[122:125], v[154:157], v[182:185], v[122:125]
	v_mfma_f32_16x16x32_bf16 v[110:113], v[146:149], v[190:193], v[110:113]
	v_mfma_f32_16x16x32_bf16 v[106:109], v[154:157], v[190:193], v[106:109]
	v_mfma_f32_16x16x32_bf16 v[94:97], v[146:149], v[198:201], v[94:97]
	v_mfma_f32_16x16x32_bf16 v[90:93], v[154:157], v[198:201], v[90:93]
	v_mfma_f32_16x16x32_bf16 v[78:81], v[146:149], v[216:219], v[78:81]
	v_mfma_f32_16x16x32_bf16 v[74:77], v[154:157], v[216:219], v[74:77]
	v_mfma_f32_16x16x32_bf16 v[126:129], v[150:153], v[186:189], v[126:129]
	v_mfma_f32_16x16x32_bf16 v[122:125], v[158:161], v[186:189], v[122:125]
	v_mfma_f32_16x16x32_bf16 v[110:113], v[150:153], v[194:197], v[110:113]
	v_mfma_f32_16x16x32_bf16 v[106:109], v[158:161], v[194:197], v[106:109]
	v_mfma_f32_16x16x32_bf16 v[94:97], v[150:153], v[202:205], v[94:97]
	v_mfma_f32_16x16x32_bf16 v[90:93], v[158:161], v[202:205], v[90:93]
	v_mfma_f32_16x16x32_bf16 v[78:81], v[150:153], v[232:235], v[78:81]
	v_mfma_f32_16x16x32_bf16 v[74:77], v[158:161], v[232:235], v[74:77]
	v_mfma_f32_16x16x32_bf16 v[118:121], v[162:165], v[182:185], v[118:121]
	v_mfma_f32_16x16x32_bf16 v[114:117], v[170:173], v[182:185], v[114:117]
	v_mfma_f32_16x16x32_bf16 v[102:105], v[162:165], v[190:193], v[102:105]
	v_mfma_f32_16x16x32_bf16 v[98:101], v[170:173], v[190:193], v[98:101]
	v_mfma_f32_16x16x32_bf16 v[86:89], v[162:165], v[198:201], v[86:89]
	v_mfma_f32_16x16x32_bf16 v[82:85], v[170:173], v[198:201], v[82:85]
	v_mfma_f32_16x16x32_bf16 v[70:73], v[162:165], v[216:219], v[70:73]
	v_mfma_f32_16x16x32_bf16 v[66:69], v[170:173], v[216:219], v[66:69]
	v_mfma_f32_16x16x32_bf16 v[118:121], v[166:169], v[186:189], v[118:121]
	v_mfma_f32_16x16x32_bf16 v[114:117], v[174:177], v[186:189], v[114:117]
	v_mfma_f32_16x16x32_bf16 v[102:105], v[166:169], v[194:197], v[102:105]
	v_mfma_f32_16x16x32_bf16 v[98:101], v[174:177], v[194:197], v[98:101]
	v_mfma_f32_16x16x32_bf16 v[86:89], v[166:169], v[202:205], v[86:89]
	v_mfma_f32_16x16x32_bf16 v[82:85], v[174:177], v[202:205], v[82:85]
	v_mfma_f32_16x16x32_bf16 v[70:73], v[166:169], v[232:235], v[70:73]
	v_mfma_f32_16x16x32_bf16 v[66:69], v[174:177], v[232:235], v[66:69]
	s_barrier
	s_add_i32 s35, s35, s50
	v_lshl_add_u64 v[178:179], s[10:11], 0, v[132:133]
	s_mov_b32 m0, s35
	ds_read_b128 v[182:185], v211 offset:16384
	ds_read_b128 v[186:189], v211 offset:17408
	ds_read_b128 v[190:193], v211 offset:18432
	ds_read_b128 v[194:197], v211 offset:19456
	ds_read_b128 v[198:201], v211 offset:20480
	ds_read_b128 v[202:205], v211 offset:21504
	ds_read_b128 v[216:219], v211 offset:22528
	ds_read_b128 v[232:235], v211 offset:23552
	global_load_lds_dwordx4 v[178:179], off
	s_add_i32 m0, s35, 0x2000
	s_add_u32 s42, s10, 0x40000
	v_lshl_add_u64 v[206:207], s[10:11], 0, v[136:137]
	s_addc_u32 s43, s11, 0
	s_add_i32 s35, s64, s50
	global_load_lds_dwordx4 v[206:207], off
	v_lshl_add_u64 v[220:221], s[42:43], 0, v[132:133]
	s_mov_b32 m0, s35
	v_lshl_add_u64 v[236:237], s[40:41], 0, v[134:135]
	global_load_lds_dwordx4 v[220:221], off
	v_lshl_add_u64 v[220:221], s[42:43], 0, v[136:137]
	s_add_i32 m0, s35, 0x2000
	s_nop 0
	global_load_lds_dwordx4 v[220:221], off
	v_lshl_add_u64 v[220:221], s[40:41], 0, v[130:131]
	s_mov_b32 m0, s51
	s_nop 0
	global_load_lds_dwordx4 v[220:221], off
	s_mov_b32 m0, s52
	s_nop 0
	global_load_lds_dwordx4 v[236:237], off
	s_waitcnt vmcnt(8)
	s_waitcnt lgkmcnt(0)
	s_barrier
; #define PG8_STAGE(bufoff, gbase, voff) do { _Pragma("unroll") for (int _i = 0; _i < 2; ++_i) \
;         __builtin_amdgcn_global_load_lds((const unsigned*)((const char*)(gbase) + (voff)[_i]), (LAS unsigned*)(lds + (bufoff) + ldsw + _i * 8192), 16, 0, 0); } while (0)
; #define PG8_LDA(dst, b, h) do { _Pragma("unroll") for (int m = 0; m < 4; ++m) _Pragma("unroll") for (int k = 0; k < 2; ++k) dst[m][k] = *(const LAS bf16x8*)(lds + PG8_SA(b, h) + aoff + m * 2048 + k * 1024); } while (0)
; #define PG8_LDB(dst, b, h) do { _Pragma("unroll") for (int n = 0; n < 2; ++n) _Pragma("unroll") for (int k = 0; k < 2; ++k) dst[n][k] = *(const LAS bf16x8*)(lds + PG8_SB(b, h) + boff + n * 2048 + k * 1024); } while (0)
; #define PG8_MMA(ai, bj, At, Bt) do { __builtin_amdgcn_s_setprio(1); _Pragma("unroll") for (int m = 0; m < 4; ++m) _Pragma("unroll") for (int n = 0; n < 2; ++n) _Pragma("unroll") for (int k = 0; k < 2; ++k) \
;         acc[ai][bj][m][n] = __builtin_amdgcn_mfma_f32_16x16x32_bf16(Bt[n][k], At[m][k], acc[ai][bj][m][n], 0, 0, 0); __builtin_amdgcn_s_setprio(0); } while (0)
; #define PG8_WAIT_V(n) asm volatile("s_waitcnt vmcnt(" #n ")" ::: "memory")
; #define PG8_WAIT_L(n) asm volatile("s_waitcnt lgkmcnt(" #n ")" ::: "memory")
; #define PG8_BAR __builtin_amdgcn_s_barrier()
; #define PG8_SCHED __builtin_amdgcn_sched_barrier(0)
; template <class Epi>
; __device__ __forceinline__ void gemm_phase(LAS unsigned char* lds, const Gemm g, const StaticOrder& S, const Epi& E) {
;     ...
;             PG8_WAIT_V(8); PG8_WAIT_L(0); PG8_BAR; PG8_MMA(0, 0, At, B0); PG8_MMA(0, 1, At, B1); PG8_BAR; PG8_SCHED;
;             PG8_LDA(At, 0, 1); PG8_STAGE(PG8_SB(0, 0), b2, voffB); PG8_STAGE(PG8_SB(0, 1), b2 + hB, voffB); PG8_STAGE(PG8_SA(0, 0), a2, voffA);
;             PG8_WAIT_V(8); PG8_WAIT_L(0); PG8_BAR; PG8_MMA(1, 0, At, B0); PG8_MMA(1, 1, At, B1); PG8_BAR; PG8_SCHED;
;             PG8_LDB(B0, 1, 0); PG8_LDB(B1, 1, 1); PG8_SCHED; PG8_LDA(At, 1, 0); PG8_STAGE(PG8_SA(0, 1), a2 + hA, voffA);
;             PG8_WAIT_V(8); PG8_WAIT_L(0); PG8_BAR; PG8_MMA(0, 0, At, B0); PG8_MMA(0, 1, At, B1); PG8_BAR; PG8_SCHED;
	v_mfma_f32_16x16x32_bf16 v[62:65], v[146:149], v[182:185], v[62:65]
	v_mfma_f32_16x16x32_bf16 v[58:61], v[154:157], v[182:185], v[58:61]
	v_mfma_f32_16x16x32_bf16 v[46:49], v[146:149], v[190:193], v[46:49]
	v_mfma_f32_16x16x32_bf16 v[42:45], v[154:157], v[190:193], v[42:45]
	v_mfma_f32_16x16x32_bf16 v[30:33], v[146:149], v[198:201], v[30:33]
	v_mfma_f32_16x16x32_bf16 v[26:29], v[154:157], v[198:201], v[26:29]
	v_mfma_f32_16x16x32_bf16 v[14:17], v[146:149], v[216:219], v[14:17]
	v_mfma_f32_16x16x32_bf16 v[10:13], v[154:157], v[216:219], v[10:13]
	v_mfma_f32_16x16x32_bf16 v[62:65], v[150:153], v[186:189], v[62:65]
	v_mfma_f32_16x16x32_bf16 v[58:61], v[158:161], v[186:189], v[58:61]
	v_mfma_f32_16x16x32_bf16 v[46:49], v[150:153], v[194:197], v[46:49]
	v_mfma_f32_16x16x32_bf16 v[42:45], v[158:161], v[194:197], v[42:45]
	v_mfma_f32_16x16x32_bf16 v[30:33], v[150:153], v[202:205], v[30:33]
	v_mfma_f32_16x16x32_bf16 v[26:29], v[158:161], v[202:205], v[26:29]
	v_mfma_f32_16x16x32_bf16 v[14:17], v[150:153], v[232:235], v[14:17]
	v_mfma_f32_16x16x32_bf16 v[10:13], v[158:161], v[232:235], v[10:13]
	v_mfma_f32_16x16x32_bf16 v[54:57], v[162:165], v[182:185], v[54:57]
	v_mfma_f32_16x16x32_bf16 v[50:53], v[170:173], v[182:185], v[50:53]
	v_mfma_f32_16x16x32_bf16 v[38:41], v[162:165], v[190:193], v[38:41]
	v_mfma_f32_16x16x32_bf16 v[34:37], v[170:173], v[190:193], v[34:37]
	v_mfma_f32_16x16x32_bf16 v[22:25], v[162:165], v[198:201], v[22:25]
	v_mfma_f32_16x16x32_bf16 v[18:21], v[170:173], v[198:201], v[18:21]
	v_mfma_f32_16x16x32_bf16 v[6:9], v[162:165], v[216:219], v[6:9]
	v_mfma_f32_16x16x32_bf16 v[2:5], v[170:173], v[216:219], v[2:5]
	v_mfma_f32_16x16x32_bf16 v[54:57], v[166:169], v[186:189], v[54:57]
	v_mfma_f32_16x16x32_bf16 v[50:53], v[174:177], v[186:189], v[50:53]
	v_mfma_f32_16x16x32_bf16 v[38:41], v[166:169], v[194:197], v[38:41]
	v_mfma_f32_16x16x32_bf16 v[34:37], v[174:177], v[194:197], v[34:37]
	v_mfma_f32_16x16x32_bf16 v[22:25], v[166:169], v[202:205], v[22:25]
	v_mfma_f32_16x16x32_bf16 v[18:21], v[174:177], v[202:205], v[18:21]
	v_mfma_f32_16x16x32_bf16 v[6:9], v[166:169], v[232:235], v[6:9]
	v_mfma_f32_16x16x32_bf16 v[2:5], v[174:177], v[232:235], v[2:5]
	s_barrier
	s_add_i32 s35, 0, 0x18000
	s_add_i32 s42, 0, 0x1c000
	v_add_u32_e32 v158, s35, v180
	v_add_u32_e32 v174, s42, v180
	ds_read_b128 v[146:149], v158
	ds_read_b128 v[150:153], v158 offset:1024
	ds_read_b128 v[154:157], v158 offset:2048
	ds_read_b128 v[158:161], v158 offset:3072
	ds_read_b128 v[162:165], v174
	ds_read_b128 v[166:169], v174 offset:1024
	ds_read_b128 v[170:173], v174 offset:2048
	ds_read_b128 v[174:177], v174 offset:3072
	s_add_u32 s40, s40, 0x40000
	s_addc_u32 s41, s41, 0
	s_mov_b32 m0, s53
	v_lshl_add_u64 v[238:239], s[40:41], 0, v[130:131]
	ds_read_b128 v[182:185], v211 offset:32768
	ds_read_b128 v[186:189], v211 offset:33792
	ds_read_b128 v[190:193], v211 offset:34816
	ds_read_b128 v[194:197], v211 offset:35840
	ds_read_b128 v[198:201], v211 offset:36864
	ds_read_b128 v[202:205], v211 offset:37888
	ds_read_b128 v[216:219], v211 offset:38912
	ds_read_b128 v[232:235], v211 offset:39936
	global_load_lds_dwordx4 v[238:239], off
	v_lshl_add_u64 v[238:239], s[40:41], 0, v[134:135]
	s_mov_b32 m0, s54
	s_nop 0
	global_load_lds_dwordx4 v[238:239], off
	s_waitcnt vmcnt(8)
	s_waitcnt lgkmcnt(0)
	s_barrier
	v_mfma_f32_16x16x32_bf16 v[126:129], v[146:149], v[182:185], v[126:129]
	v_mfma_f32_16x16x32_bf16 v[122:125], v[154:157], v[182:185], v[122:125]
	v_mfma_f32_16x16x32_bf16 v[110:113], v[146:149], v[190:193], v[110:113]
	v_mfma_f32_16x16x32_bf16 v[106:109], v[154:157], v[190:193], v[106:109]
	v_mfma_f32_16x16x32_bf16 v[94:97], v[146:149], v[198:201], v[94:97]
	v_mfma_f32_16x16x32_bf16 v[90:93], v[154:157], v[198:201], v[90:93]
	v_mfma_f32_16x16x32_bf16 v[78:81], v[146:149], v[216:219], v[78:81]
	v_mfma_f32_16x16x32_bf16 v[74:77], v[154:157], v[216:219], v[74:77]
	v_mfma_f32_16x16x32_bf16 v[126:129], v[150:153], v[186:189], v[126:129]
	v_mfma_f32_16x16x32_bf16 v[122:125], v[158:161], v[186:189], v[122:125]
	v_mfma_f32_16x16x32_bf16 v[110:113], v[150:153], v[194:197], v[110:113]
	v_mfma_f32_16x16x32_bf16 v[106:109], v[158:161], v[194:197], v[106:109]
	v_mfma_f32_16x16x32_bf16 v[94:97], v[150:153], v[202:205], v[94:97]
	v_mfma_f32_16x16x32_bf16 v[90:93], v[158:161], v[202:205], v[90:93]
	v_mfma_f32_16x16x32_bf16 v[78:81], v[150:153], v[232:235], v[78:81]
	v_mfma_f32_16x16x32_bf16 v[74:77], v[158:161], v[232:235], v[74:77]
	v_mfma_f32_16x16x32_bf16 v[118:121], v[162:165], v[182:185], v[118:121]
	v_mfma_f32_16x16x32_bf16 v[114:117], v[170:173], v[182:185], v[114:117]
	v_mfma_f32_16x16x32_bf16 v[102:105], v[162:165], v[190:193], v[102:105]
	v_mfma_f32_16x16x32_bf16 v[98:101], v[170:173], v[190:193], v[98:101]
	v_mfma_f32_16x16x32_bf16 v[86:89], v[162:165], v[198:201], v[86:89]
	v_mfma_f32_16x16x32_bf16 v[82:85], v[170:173], v[198:201], v[82:85]
	v_mfma_f32_16x16x32_bf16 v[70:73], v[162:165], v[216:219], v[70:73]
	v_mfma_f32_16x16x32_bf16 v[66:69], v[170:173], v[216:219], v[66:69]
	v_mfma_f32_16x16x32_bf16 v[118:121], v[166:169], v[186:189], v[118:121]
	v_mfma_f32_16x16x32_bf16 v[114:117], v[174:177], v[186:189], v[114:117]
	v_mfma_f32_16x16x32_bf16 v[102:105], v[166:169], v[194:197], v[102:105]
	v_mfma_f32_16x16x32_bf16 v[98:101], v[174:177], v[194:197], v[98:101]
	v_mfma_f32_16x16x32_bf16 v[86:89], v[166:169], v[202:205], v[86:89]
	v_mfma_f32_16x16x32_bf16 v[82:85], v[174:177], v[202:205], v[82:85]
	v_mfma_f32_16x16x32_bf16 v[70:73], v[166:169], v[232:235], v[70:73]
	v_mfma_f32_16x16x32_bf16 v[66:69], v[174:177], v[232:235], v[66:69]
	s_barrier
; #define PG8_STAGE(bufoff, gbase, voff) do { _Pragma("unroll") for (int _i = 0; _i < 2; ++_i) \
;         __builtin_amdgcn_global_load_lds((const unsigned*)((const char*)(gbase) + (voff)[_i]), (LAS unsigned*)(lds + (bufoff) + ldsw + _i * 8192), 16, 0, 0); } while (0)
; #define PG8_LDA(dst, b, h) do { _Pragma("unroll") for (int m = 0; m < 4; ++m) _Pragma("unroll") for (int k = 0; k < 2; ++k) dst[m][k] = *(const LAS bf16x8*)(lds + PG8_SA(b, h) + aoff + m * 2048 + k * 1024); } while (0)
; #define PG8_MMA(ai, bj, At, Bt) do { __builtin_amdgcn_s_setprio(1); _Pragma("unroll") for (int m = 0; m < 4; ++m) _Pragma("unroll") for (int n = 0; n < 2; ++n) _Pragma("unroll") for (int k = 0; k < 2; ++k) \
;         acc[ai][bj][m][n] = __builtin_amdgcn_mfma_f32_16x16x32_bf16(Bt[n][k], At[m][k], acc[ai][bj][m][n], 0, 0, 0); __builtin_amdgcn_s_setprio(0); } while (0)
; #define PG8_WAIT_V(n) asm volatile("s_waitcnt vmcnt(" #n ")" ::: "memory")
; #define PG8_WAIT_L(n) asm volatile("s_waitcnt lgkmcnt(" #n ")" ::: "memory")
; #define PG8_BAR __builtin_amdgcn_s_barrier()
; #define PG8_SCHED __builtin_amdgcn_sched_barrier(0)
; template <class Epi>
; __device__ __forceinline__ void gemm_phase(LAS unsigned char* lds, const Gemm g, const StaticOrder& S, const Epi& E) {
;     ...
;             PG8_LDA(At, 1, 1); PG8_STAGE(PG8_SB(1, 0), b3, voffB); PG8_STAGE(PG8_SB(1, 1), b3 + hB, voffB); PG8_STAGE(PG8_SA(1, 0), a3, voffA);
;             PG8_WAIT_V(8); PG8_WAIT_L(0); PG8_BAR; PG8_MMA(1, 0, At, B0); PG8_MMA(1, 1, At, B1); PG8_BAR; PG8_SCHED;
;         }
;         if (wr == 0) PG8_BAR;
	s_add_i32 s35, s35, s50
	v_lshl_add_u64 v[178:179], v[178:179], 0, s[88:89]
	s_mov_b32 m0, s35
	ds_read_b128 v[182:185], v211 offset:49152
	ds_read_b128 v[186:189], v211 offset:50176
	ds_read_b128 v[190:193], v211 offset:51200
	ds_read_b128 v[194:197], v211 offset:52224
	ds_read_b128 v[198:201], v211 offset:53248
	ds_read_b128 v[202:205], v211 offset:54272
	ds_read_b128 v[216:219], v211 offset:55296
	ds_read_b128 v[232:235], v211 offset:56320
	global_load_lds_dwordx4 v[178:179], off
	s_add_i32 m0, s35, 0x2000
	s_add_u32 s10, s10, 0x40080
	v_lshl_add_u64 v[178:179], v[206:207], 0, s[88:89]
	s_addc_u32 s11, s11, 0
	s_add_i32 s35, s42, s50
	global_load_lds_dwordx4 v[178:179], off
	v_lshl_add_u64 v[178:179], s[10:11], 0, v[132:133]
	s_mov_b32 m0, s35
	s_nop 0
	global_load_lds_dwordx4 v[178:179], off
	v_lshl_add_u64 v[178:179], s[10:11], 0, v[136:137]
	s_add_i32 m0, s35, 0x2000
	s_nop 0
	global_load_lds_dwordx4 v[178:179], off
	v_lshl_add_u64 v[178:179], v[220:221], 0, s[88:89]
	s_mov_b32 m0, s55
	s_nop 0
	global_load_lds_dwordx4 v[178:179], off
	v_lshl_add_u64 v[178:179], v[236:237], 0, s[88:89]
	s_mov_b32 m0, s56
	s_nop 0
	global_load_lds_dwordx4 v[178:179], off
	s_waitcnt vmcnt(8)
	s_waitcnt lgkmcnt(0)
	s_barrier
	v_mfma_f32_16x16x32_bf16 v[62:65], v[146:149], v[182:185], v[62:65]
	v_mfma_f32_16x16x32_bf16 v[58:61], v[154:157], v[182:185], v[58:61]
	v_mfma_f32_16x16x32_bf16 v[46:49], v[146:149], v[190:193], v[46:49]
	v_mfma_f32_16x16x32_bf16 v[42:45], v[154:157], v[190:193], v[42:45]
	v_mfma_f32_16x16x32_bf16 v[30:33], v[146:149], v[198:201], v[30:33]
	v_mfma_f32_16x16x32_bf16 v[26:29], v[154:157], v[198:201], v[26:29]
	v_mfma_f32_16x16x32_bf16 v[14:17], v[146:149], v[216:219], v[14:17]
	v_mfma_f32_16x16x32_bf16 v[10:13], v[154:157], v[216:219], v[10:13]
	v_mfma_f32_16x16x32_bf16 v[62:65], v[150:153], v[186:189], v[62:65]
	v_mfma_f32_16x16x32_bf16 v[58:61], v[158:161], v[186:189], v[58:61]
	v_mfma_f32_16x16x32_bf16 v[46:49], v[150:153], v[194:197], v[46:49]
	v_mfma_f32_16x16x32_bf16 v[42:45], v[158:161], v[194:197], v[42:45]
	v_mfma_f32_16x16x32_bf16 v[30:33], v[150:153], v[202:205], v[30:33]
	v_mfma_f32_16x16x32_bf16 v[26:29], v[158:161], v[202:205], v[26:29]
	v_mfma_f32_16x16x32_bf16 v[14:17], v[150:153], v[232:235], v[14:17]
	v_mfma_f32_16x16x32_bf16 v[10:13], v[158:161], v[232:235], v[10:13]
	v_mfma_f32_16x16x32_bf16 v[54:57], v[162:165], v[182:185], v[54:57]
	v_mfma_f32_16x16x32_bf16 v[50:53], v[170:173], v[182:185], v[50:53]
	v_mfma_f32_16x16x32_bf16 v[38:41], v[162:165], v[190:193], v[38:41]
	v_mfma_f32_16x16x32_bf16 v[34:37], v[170:173], v[190:193], v[34:37]
	v_mfma_f32_16x16x32_bf16 v[22:25], v[162:165], v[198:201], v[22:25]
	v_mfma_f32_16x16x32_bf16 v[18:21], v[170:173], v[198:201], v[18:21]
	v_mfma_f32_16x16x32_bf16 v[6:9], v[162:165], v[216:219], v[6:9]
	v_mfma_f32_16x16x32_bf16 v[2:5], v[170:173], v[216:219], v[2:5]
	v_mfma_f32_16x16x32_bf16 v[54:57], v[166:169], v[186:189], v[54:57]
	v_mfma_f32_16x16x32_bf16 v[50:53], v[174:177], v[186:189], v[50:53]
	v_mfma_f32_16x16x32_bf16 v[38:41], v[166:169], v[194:197], v[38:41]
	v_mfma_f32_16x16x32_bf16 v[34:37], v[174:177], v[194:197], v[34:37]
	v_mfma_f32_16x16x32_bf16 v[22:25], v[166:169], v[202:205], v[22:25]
	v_mfma_f32_16x16x32_bf16 v[18:21], v[174:177], v[202:205], v[18:21]
	v_mfma_f32_16x16x32_bf16 v[6:9], v[166:169], v[232:235], v[6:9]
	v_mfma_f32_16x16x32_bf16 v[2:5], v[174:177], v[232:235], v[2:5]
	s_barrier
	s_add_i32 s31, s31, 2
	s_add_u32 s8, s8, 0x100
	s_addc_u32 s9, s9, 0
	s_add_u32 s27, s27, 0x100
	s_addc_u32 s29, s29, 0
	s_cmp_gt_u32 s31, 13
	s_cbranch_scc0 .LBB0_1398
	s_and_b64 vcc, exec, s[16:17]
	s_cbranch_vccz .LBB0_1401
	s_barrier

; #define PG8_STAGE(bufoff, gbase, voff) do { _Pragma("unroll") for (int _i = 0; _i < 2; ++_i) \
;         __builtin_amdgcn_global_load_lds((const unsigned*)((const char*)(gbase) + (voff)[_i]), (LAS unsigned*)(lds + (bufoff) + ldsw + _i * 8192), 16, 0, 0); } while (0)
; #define PG8_LDA(dst, b, h) do { _Pragma("unroll") for (int m = 0; m < 4; ++m) _Pragma("unroll") for (int k = 0; k < 2; ++k) dst[m][k] = *(const LAS bf16x8*)(lds + PG8_SA(b, h) + aoff + m * 2048 + k * 1024); } while (0)
; #define PG8_LDB(dst, b, h) do { _Pragma("unroll") for (int n = 0; n < 2; ++n) _Pragma("unroll") for (int k = 0; k < 2; ++k) dst[n][k] = *(const LAS bf16x8*)(lds + PG8_SB(b, h) + boff + n * 2048 + k * 1024); } while (0)
; #define PG8_MMA(ai, bj, At, Bt) do { __builtin_amdgcn_s_setprio(1); _Pragma("unroll") for (int m = 0; m < 4; ++m) _Pragma("unroll") for (int n = 0; n < 2; ++n) _Pragma("unroll") for (int k = 0; k < 2; ++k) \
;         acc[ai][bj][m][n] = __builtin_amdgcn_mfma_f32_16x16x32_bf16(Bt[n][k], At[m][k], acc[ai][bj][m][n], 0, 0, 0); __builtin_amdgcn_s_setprio(0); } while (0)
; #define PG8_WAIT_V(n) asm volatile("s_waitcnt vmcnt(" #n ")" ::: "memory")
; #define PG8_WAIT_L(n) asm volatile("s_waitcnt lgkmcnt(" #n ")" ::: "memory")
; #define PG8_BAR __builtin_amdgcn_s_barrier()
; #define PG8_SCHED __builtin_amdgcn_sched_barrier(0)
; template <class Epi>
; __device__ __forceinline__ void gemm_phase(LAS unsigned char* lds, const Gemm g, const StaticOrder& S, const Epi& E) {
;     ...
;             PG8_LDB(B0, 0, 0); PG8_LDB(B1, 0, 1); PG8_SCHED; PG8_LDA(At, 0, 0); PG8_STAGE(PG8_SA(1, 1), a1 + hA, voffA);
;             PG8_WAIT_V(8); PG8_WAIT_L(0); PG8_BAR; PG8_MMA(0, 0, At, B0); PG8_MMA(0, 1, At, B1); PG8_BAR; PG8_SCHED;
;             PG8_LDA(At, 0, 1); PG8_STAGE(PG8_SB(0, 0), b2, voffB); PG8_STAGE(PG8_SB(0, 1), b2 + hB, voffB); PG8_STAGE(PG8_SA(0, 0), a2, voffA);
;             PG8_WAIT_V(8); PG8_WAIT_L(0); PG8_BAR; PG8_MMA(1, 0, At, B0); PG8_MMA(1, 1, At, B1); PG8_BAR; PG8_SCHED;
.LBB0_1550:
	s_add_u32 s22, s20, 0xfffc0080
	s_addc_u32 s23, s21, -1
	s_add_i32 s51, 0, 0x10000
	s_cmp_eq_u32 s50, 12
	s_cselect_b32 s25, s15, s23
	s_cselect_b32 s24, s46, s22
	v_add_u32_e32 v142, s51, v143
	s_cselect_b32 s23, s13, s49
	s_cselect_b32 s22, s47, s48
	s_add_i32 s54, 0, 0x14000
	ds_read_b128 v[148:151], v142
	ds_read_b128 v[152:155], v142 offset:1024
	ds_read_b128 v[156:159], v142 offset:2048
	ds_read_b128 v[160:163], v142 offset:3072
	v_add_u32_e32 v142, s54, v143
	ds_read_b128 v[164:167], v142
	ds_read_b128 v[168:171], v142 offset:1024
	ds_read_b128 v[172:175], v142 offset:2048
	ds_read_b128 v[176:179], v142 offset:3072
	v_lshl_add_u64 v[214:215], s[20:21], 0, v[138:139]
	s_add_i32 m0, s34, 0xc000
	ds_read_b128 v[182:185], v147
	ds_read_b128 v[186:189], v147 offset:1024
	ds_read_b128 v[190:193], v147 offset:2048
	ds_read_b128 v[194:197], v147 offset:3072
	ds_read_b128 v[198:201], v147 offset:4096
	ds_read_b128 v[202:205], v147 offset:5120
	ds_read_b128 v[206:209], v147 offset:6144
	ds_read_b128 v[210:213], v147 offset:7168
	global_load_lds_dwordx4 v[214:215], off
	v_lshl_add_u64 v[214:215], s[20:21], 0, v[140:141]
	s_add_i32 m0, s34, 0xe000
	s_nop 0
	global_load_lds_dwordx4 v[214:215], off
	s_waitcnt vmcnt(8)
	s_waitcnt lgkmcnt(0)
	s_barrier
	v_mfma_f32_16x16x32_bf16 v[126:129], v[148:151], v[182:185], v[126:129]
	v_mfma_f32_16x16x32_bf16 v[122:125], v[156:159], v[182:185], v[122:125]
	v_mfma_f32_16x16x32_bf16 v[110:113], v[148:151], v[190:193], v[110:113]
	v_mfma_f32_16x16x32_bf16 v[106:109], v[156:159], v[190:193], v[106:109]
	v_mfma_f32_16x16x32_bf16 v[94:97], v[148:151], v[198:201], v[94:97]
	v_mfma_f32_16x16x32_bf16 v[90:93], v[156:159], v[198:201], v[90:93]
	v_mfma_f32_16x16x32_bf16 v[78:81], v[148:151], v[206:209], v[78:81]
	v_mfma_f32_16x16x32_bf16 v[74:77], v[156:159], v[206:209], v[74:77]
	v_mfma_f32_16x16x32_bf16 v[126:129], v[152:155], v[186:189], v[126:129]
	v_mfma_f32_16x16x32_bf16 v[122:125], v[160:163], v[186:189], v[122:125]
	v_mfma_f32_16x16x32_bf16 v[110:113], v[152:155], v[194:197], v[110:113]
	v_mfma_f32_16x16x32_bf16 v[106:109], v[160:163], v[194:197], v[106:109]
	v_mfma_f32_16x16x32_bf16 v[94:97], v[152:155], v[202:205], v[94:97]
	v_mfma_f32_16x16x32_bf16 v[90:93], v[160:163], v[202:205], v[90:93]
	v_mfma_f32_16x16x32_bf16 v[78:81], v[152:155], v[210:213], v[78:81]
	v_mfma_f32_16x16x32_bf16 v[74:77], v[160:163], v[210:213], v[74:77]
	v_mfma_f32_16x16x32_bf16 v[118:121], v[164:167], v[182:185], v[118:121]
	v_mfma_f32_16x16x32_bf16 v[114:117], v[172:175], v[182:185], v[114:117]
	v_mfma_f32_16x16x32_bf16 v[102:105], v[164:167], v[190:193], v[102:105]
	v_mfma_f32_16x16x32_bf16 v[98:101], v[172:175], v[190:193], v[98:101]
	v_mfma_f32_16x16x32_bf16 v[86:89], v[164:167], v[198:201], v[86:89]
	v_mfma_f32_16x16x32_bf16 v[82:85], v[172:175], v[198:201], v[82:85]
	v_mfma_f32_16x16x32_bf16 v[70:73], v[164:167], v[206:209], v[70:73]
	v_mfma_f32_16x16x32_bf16 v[66:69], v[172:175], v[206:209], v[66:69]
	v_mfma_f32_16x16x32_bf16 v[118:121], v[168:171], v[186:189], v[118:121]
	v_mfma_f32_16x16x32_bf16 v[114:117], v[176:179], v[186:189], v[114:117]
	v_mfma_f32_16x16x32_bf16 v[102:105], v[168:171], v[194:197], v[102:105]
	v_mfma_f32_16x16x32_bf16 v[98:101], v[176:179], v[194:197], v[98:101]
	v_mfma_f32_16x16x32_bf16 v[86:89], v[168:171], v[202:205], v[86:89]
	v_mfma_f32_16x16x32_bf16 v[82:85], v[176:179], v[202:205], v[82:85]
	v_mfma_f32_16x16x32_bf16 v[70:73], v[168:171], v[210:213], v[70:73]
	v_mfma_f32_16x16x32_bf16 v[66:69], v[176:179], v[210:213], v[66:69]
	s_barrier
	s_add_i32 s51, s51, s31
	v_lshl_add_u64 v[214:215], s[22:23], 0, v[134:135]
	s_mov_b32 m0, s51
	ds_read_b128 v[182:185], v147 offset:16384
	ds_read_b128 v[186:189], v147 offset:17408
	ds_read_b128 v[190:193], v147 offset:18432
	ds_read_b128 v[194:197], v147 offset:19456
	ds_read_b128 v[198:201], v147 offset:20480
	ds_read_b128 v[202:205], v147 offset:21504
	ds_read_b128 v[206:209], v147 offset:22528
	ds_read_b128 v[210:213], v147 offset:23552
	global_load_lds_dwordx4 v[214:215], off
	s_add_i32 m0, s51, 0x2000
	s_add_u32 s52, s22, 0x40000
	v_lshl_add_u64 v[216:217], s[22:23], 0, v[130:131]
	s_addc_u32 s53, s23, 0
	s_add_i32 s51, s54, s31
	global_load_lds_dwordx4 v[216:217], off
	v_lshl_add_u64 v[218:219], s[52:53], 0, v[134:135]
	s_mov_b32 m0, s51
	v_lshl_add_u64 v[220:221], s[24:25], 0, v[132:133]
	global_load_lds_dwordx4 v[218:219], off
	v_lshl_add_u64 v[218:219], s[52:53], 0, v[130:131]
	s_add_i32 m0, s51, 0x2000
	s_nop 0
	global_load_lds_dwordx4 v[218:219], off
	v_lshl_add_u64 v[218:219], s[24:25], 0, v[136:137]
	s_mov_b32 m0, s34
	s_nop 0
	global_load_lds_dwordx4 v[218:219], off
	s_mov_b32 m0, s35
	s_nop 0
	global_load_lds_dwordx4 v[220:221], off
	s_waitcnt vmcnt(8)
	s_waitcnt lgkmcnt(0)
	s_barrier
; #define PG8_STAGE(bufoff, gbase, voff) do { _Pragma("unroll") for (int _i = 0; _i < 2; ++_i) \
;         __builtin_amdgcn_global_load_lds((const unsigned*)((const char*)(gbase) + (voff)[_i]), (LAS unsigned*)(lds + (bufoff) + ldsw + _i * 8192), 16, 0, 0); } while (0)
; #define PG8_LDA(dst, b, h) do { _Pragma("unroll") for (int m = 0; m < 4; ++m) _Pragma("unroll") for (int k = 0; k < 2; ++k) dst[m][k] = *(const LAS bf16x8*)(lds + PG8_SA(b, h) + aoff + m * 2048 + k * 1024); } while (0)
; #define PG8_LDB(dst, b, h) do { _Pragma("unroll") for (int n = 0; n < 2; ++n) _Pragma("unroll") for (int k = 0; k < 2; ++k) dst[n][k] = *(const LAS bf16x8*)(lds + PG8_SB(b, h) + boff + n * 2048 + k * 1024); } while (0)
; #define PG8_MMA(ai, bj, At, Bt) do { __builtin_amdgcn_s_setprio(1); _Pragma("unroll") for (int m = 0; m < 4; ++m) _Pragma("unroll") for (int n = 0; n < 2; ++n) _Pragma("unroll") for (int k = 0; k < 2; ++k) \
;         acc[ai][bj][m][n] = __builtin_amdgcn_mfma_f32_16x16x32_bf16(Bt[n][k], At[m][k], acc[ai][bj][m][n], 0, 0, 0); __builtin_amdgcn_s_setprio(0); } while (0)
; #define PG8_WAIT_V(n) asm volatile("s_waitcnt vmcnt(" #n ")" ::: "memory")
; #define PG8_WAIT_L(n) asm volatile("s_waitcnt lgkmcnt(" #n ")" ::: "memory")
; #define PG8_BAR __builtin_amdgcn_s_barrier()
; #define PG8_SCHED __builtin_amdgcn_sched_barrier(0)
; template <class Epi>
; __device__ __forceinline__ void gemm_phase(LAS unsigned char* lds, const Gemm g, const StaticOrder& S, const Epi& E) {
;     ...
;             PG8_WAIT_V(8); PG8_WAIT_L(0); PG8_BAR; PG8_MMA(0, 0, At, B0); PG8_MMA(0, 1, At, B1); PG8_BAR; PG8_SCHED;
;             PG8_LDA(At, 0, 1); PG8_STAGE(PG8_SB(0, 0), b2, voffB); PG8_STAGE(PG8_SB(0, 1), b2 + hB, voffB); PG8_STAGE(PG8_SA(0, 0), a2, voffA);
;             PG8_WAIT_V(8); PG8_WAIT_L(0); PG8_BAR; PG8_MMA(1, 0, At, B0); PG8_MMA(1, 1, At, B1); PG8_BAR; PG8_SCHED;
;             PG8_LDB(B0, 1, 0); PG8_LDB(B1, 1, 1); PG8_SCHED; PG8_LDA(At, 1, 0); PG8_STAGE(PG8_SA(0, 1), a2 + hA, voffA);
;             PG8_WAIT_V(8); PG8_WAIT_L(0); PG8_BAR; PG8_MMA(0, 0, At, B0); PG8_MMA(0, 1, At, B1); PG8_BAR; PG8_SCHED;
	v_mfma_f32_16x16x32_bf16 v[62:65], v[148:151], v[182:185], v[62:65]
	v_mfma_f32_16x16x32_bf16 v[58:61], v[156:159], v[182:185], v[58:61]
	v_mfma_f32_16x16x32_bf16 v[46:49], v[148:151], v[190:193], v[46:49]
	v_mfma_f32_16x16x32_bf16 v[42:45], v[156:159], v[190:193], v[42:45]
	v_mfma_f32_16x16x32_bf16 v[30:33], v[148:151], v[198:201], v[30:33]
	v_mfma_f32_16x16x32_bf16 v[26:29], v[156:159], v[198:201], v[26:29]
	v_mfma_f32_16x16x32_bf16 v[14:17], v[148:151], v[206:209], v[14:17]
	v_mfma_f32_16x16x32_bf16 v[10:13], v[156:159], v[206:209], v[10:13]
	v_mfma_f32_16x16x32_bf16 v[62:65], v[152:155], v[186:189], v[62:65]
	v_mfma_f32_16x16x32_bf16 v[58:61], v[160:163], v[186:189], v[58:61]
	v_mfma_f32_16x16x32_bf16 v[46:49], v[152:155], v[194:197], v[46:49]
	v_mfma_f32_16x16x32_bf16 v[42:45], v[160:163], v[194:197], v[42:45]
	v_mfma_f32_16x16x32_bf16 v[30:33], v[152:155], v[202:205], v[30:33]
	v_mfma_f32_16x16x32_bf16 v[26:29], v[160:163], v[202:205], v[26:29]
	v_mfma_f32_16x16x32_bf16 v[14:17], v[152:155], v[210:213], v[14:17]
	v_mfma_f32_16x16x32_bf16 v[10:13], v[160:163], v[210:213], v[10:13]
	v_mfma_f32_16x16x32_bf16 v[54:57], v[164:167], v[182:185], v[54:57]
	v_mfma_f32_16x16x32_bf16 v[50:53], v[172:175], v[182:185], v[50:53]
	v_mfma_f32_16x16x32_bf16 v[38:41], v[164:167], v[190:193], v[38:41]
	v_mfma_f32_16x16x32_bf16 v[34:37], v[172:175], v[190:193], v[34:37]
	v_mfma_f32_16x16x32_bf16 v[22:25], v[164:167], v[198:201], v[22:25]
	v_mfma_f32_16x16x32_bf16 v[18:21], v[172:175], v[198:201], v[18:21]
	v_mfma_f32_16x16x32_bf16 v[6:9], v[164:167], v[206:209], v[6:9]
	v_mfma_f32_16x16x32_bf16 v[2:5], v[172:175], v[206:209], v[2:5]
	v_mfma_f32_16x16x32_bf16 v[54:57], v[168:171], v[186:189], v[54:57]
	v_mfma_f32_16x16x32_bf16 v[50:53], v[176:179], v[186:189], v[50:53]
	v_mfma_f32_16x16x32_bf16 v[38:41], v[168:171], v[194:197], v[38:41]
	v_mfma_f32_16x16x32_bf16 v[34:37], v[176:179], v[194:197], v[34:37]
	v_mfma_f32_16x16x32_bf16 v[22:25], v[168:171], v[202:205], v[22:25]
	v_mfma_f32_16x16x32_bf16 v[18:21], v[176:179], v[202:205], v[18:21]
	v_mfma_f32_16x16x32_bf16 v[6:9], v[168:171], v[210:213], v[6:9]
	v_mfma_f32_16x16x32_bf16 v[2:5], v[176:179], v[210:213], v[2:5]
	s_barrier
	s_add_i32 s51, 0, 0x18000
	v_add_u32_e32 v142, s51, v143
	s_add_i32 s52, 0, 0x1c000
	ds_read_b128 v[148:151], v142
	ds_read_b128 v[152:155], v142 offset:1024
	ds_read_b128 v[156:159], v142 offset:2048
	ds_read_b128 v[160:163], v142 offset:3072
	v_add_u32_e32 v142, s52, v143
	ds_read_b128 v[164:167], v142
	ds_read_b128 v[168:171], v142 offset:1024
	ds_read_b128 v[172:175], v142 offset:2048
	ds_read_b128 v[176:179], v142 offset:3072
	s_add_u32 s24, s24, 0x40000
	s_addc_u32 s25, s25, 0
	s_mov_b32 m0, s36
	v_lshl_add_u64 v[232:233], s[24:25], 0, v[136:137]
	ds_read_b128 v[182:185], v147 offset:32768
	ds_read_b128 v[186:189], v147 offset:33792
	ds_read_b128 v[190:193], v147 offset:34816
	ds_read_b128 v[194:197], v147 offset:35840
	ds_read_b128 v[198:201], v147 offset:36864
	ds_read_b128 v[202:205], v147 offset:37888
	ds_read_b128 v[206:209], v147 offset:38912
	ds_read_b128 v[210:213], v147 offset:39936
	global_load_lds_dwordx4 v[232:233], off
	v_lshl_add_u64 v[232:233], s[24:25], 0, v[132:133]
	s_mov_b32 m0, s37
	s_nop 0
	global_load_lds_dwordx4 v[232:233], off
	s_waitcnt vmcnt(8)
	s_waitcnt lgkmcnt(0)
	s_barrier
	v_mfma_f32_16x16x32_bf16 v[126:129], v[148:151], v[182:185], v[126:129]
	v_mfma_f32_16x16x32_bf16 v[122:125], v[156:159], v[182:185], v[122:125]
	v_mfma_f32_16x16x32_bf16 v[110:113], v[148:151], v[190:193], v[110:113]
	v_mfma_f32_16x16x32_bf16 v[106:109], v[156:159], v[190:193], v[106:109]
	v_mfma_f32_16x16x32_bf16 v[94:97], v[148:151], v[198:201], v[94:97]
	v_mfma_f32_16x16x32_bf16 v[90:93], v[156:159], v[198:201], v[90:93]
	v_mfma_f32_16x16x32_bf16 v[78:81], v[148:151], v[206:209], v[78:81]
	v_mfma_f32_16x16x32_bf16 v[74:77], v[156:159], v[206:209], v[74:77]
	v_mfma_f32_16x16x32_bf16 v[126:129], v[152:155], v[186:189], v[126:129]
	v_mfma_f32_16x16x32_bf16 v[122:125], v[160:163], v[186:189], v[122:125]
	v_mfma_f32_16x16x32_bf16 v[110:113], v[152:155], v[194:197], v[110:113]
	v_mfma_f32_16x16x32_bf16 v[106:109], v[160:163], v[194:197], v[106:109]
	v_mfma_f32_16x16x32_bf16 v[94:97], v[152:155], v[202:205], v[94:97]
	v_mfma_f32_16x16x32_bf16 v[90:93], v[160:163], v[202:205], v[90:93]
	v_mfma_f32_16x16x32_bf16 v[78:81], v[152:155], v[210:213], v[78:81]
	v_mfma_f32_16x16x32_bf16 v[74:77], v[160:163], v[210:213], v[74:77]
	v_mfma_f32_16x16x32_bf16 v[118:121], v[164:167], v[182:185], v[118:121]
	v_mfma_f32_16x16x32_bf16 v[114:117], v[172:175], v[182:185], v[114:117]
	v_mfma_f32_16x16x32_bf16 v[102:105], v[164:167], v[190:193], v[102:105]
	v_mfma_f32_16x16x32_bf16 v[98:101], v[172:175], v[190:193], v[98:101]
	v_mfma_f32_16x16x32_bf16 v[86:89], v[164:167], v[198:201], v[86:89]
	v_mfma_f32_16x16x32_bf16 v[82:85], v[172:175], v[198:201], v[82:85]
	v_mfma_f32_16x16x32_bf16 v[70:73], v[164:167], v[206:209], v[70:73]
	v_mfma_f32_16x16x32_bf16 v[66:69], v[172:175], v[206:209], v[66:69]
	v_mfma_f32_16x16x32_bf16 v[118:121], v[168:171], v[186:189], v[118:121]
	v_mfma_f32_16x16x32_bf16 v[114:117], v[176:179], v[186:189], v[114:117]
	v_mfma_f32_16x16x32_bf16 v[102:105], v[168:171], v[194:197], v[102:105]
	v_mfma_f32_16x16x32_bf16 v[98:101], v[176:179], v[194:197], v[98:101]
	v_mfma_f32_16x16x32_bf16 v[86:89], v[168:171], v[202:205], v[86:89]
	v_mfma_f32_16x16x32_bf16 v[82:85], v[176:179], v[202:205], v[82:85]
	v_mfma_f32_16x16x32_bf16 v[70:73], v[168:171], v[210:213], v[70:73]
	v_mfma_f32_16x16x32_bf16 v[66:69], v[176:179], v[210:213], v[66:69]
	s_barrier
; #define PG8_STAGE(bufoff, gbase, voff) do { _Pragma("unroll") for (int _i = 0; _i < 2; ++_i) \
;         __builtin_amdgcn_global_load_lds((const unsigned*)((const char*)(gbase) + (voff)[_i]), (LAS unsigned*)(lds + (bufoff) + ldsw + _i * 8192), 16, 0, 0); } while (0)
; #define PG8_LDA(dst, b, h) do { _Pragma("unroll") for (int m = 0; m < 4; ++m) _Pragma("unroll") for (int k = 0; k < 2; ++k) dst[m][k] = *(const LAS bf16x8*)(lds + PG8_SA(b, h) + aoff + m * 2048 + k * 1024); } while (0)
; #define PG8_MMA(ai, bj, At, Bt) do { __builtin_amdgcn_s_setprio(1); _Pragma("unroll") for (int m = 0; m < 4; ++m) _Pragma("unroll") for (int n = 0; n < 2; ++n) _Pragma("unroll") for (int k = 0; k < 2; ++k) \
;         acc[ai][bj][m][n] = __builtin_amdgcn_mfma_f32_16x16x32_bf16(Bt[n][k], At[m][k], acc[ai][bj][m][n], 0, 0, 0); __builtin_amdgcn_s_setprio(0); } while (0)
; #define PG8_WAIT_V(n) asm volatile("s_waitcnt vmcnt(" #n ")" ::: "memory")
; #define PG8_WAIT_L(n) asm volatile("s_waitcnt lgkmcnt(" #n ")" ::: "memory")
; #define PG8_BAR __builtin_amdgcn_s_barrier()
; #define PG8_SCHED __builtin_amdgcn_sched_barrier(0)
; template <class Epi>
; __device__ __forceinline__ void gemm_phase(LAS unsigned char* lds, const Gemm g, const StaticOrder& S, const Epi& E) {
;     ...
;             PG8_LDA(At, 1, 1); PG8_STAGE(PG8_SB(1, 0), b3, voffB); PG8_STAGE(PG8_SB(1, 1), b3 + hB, voffB); PG8_STAGE(PG8_SA(1, 0), a3, voffA);
;             PG8_WAIT_V(8); PG8_WAIT_L(0); PG8_BAR; PG8_MMA(1, 0, At, B0); PG8_MMA(1, 1, At, B1); PG8_BAR; PG8_SCHED;
;         }
;         if (wr == 0) PG8_BAR;
	s_add_i32 s24, s51, s31
	v_lshl_add_u64 v[214:215], v[214:215], 0, s[88:89]
	s_mov_b32 m0, s24
	ds_read_b128 v[182:185], v147 offset:49152
	ds_read_b128 v[186:189], v147 offset:50176
	ds_read_b128 v[190:193], v147 offset:51200
	ds_read_b128 v[194:197], v147 offset:52224
	ds_read_b128 v[198:201], v147 offset:53248
	ds_read_b128 v[202:205], v147 offset:54272
	ds_read_b128 v[206:209], v147 offset:55296
	ds_read_b128 v[210:213], v147 offset:56320
	global_load_lds_dwordx4 v[214:215], off
	s_add_i32 m0, s24, 0x2000
	s_add_u32 s22, s22, 0x40080
	v_lshl_add_u64 v[214:215], v[216:217], 0, s[88:89]
	s_addc_u32 s23, s23, 0
	s_add_i32 s24, s52, s31
	global_load_lds_dwordx4 v[214:215], off
	v_lshl_add_u64 v[214:215], s[22:23], 0, v[134:135]
	s_mov_b32 m0, s24
	s_nop 0
	global_load_lds_dwordx4 v[214:215], off
	v_lshl_add_u64 v[214:215], s[22:23], 0, v[130:131]
	s_add_i32 m0, s24, 0x2000
	s_nop 0
	global_load_lds_dwordx4 v[214:215], off
	v_lshl_add_u64 v[214:215], v[218:219], 0, s[88:89]
	s_mov_b32 m0, s38
	s_nop 0
	global_load_lds_dwordx4 v[214:215], off
	v_lshl_add_u64 v[214:215], v[220:221], 0, s[88:89]
	s_mov_b32 m0, s39
	s_nop 0
	global_load_lds_dwordx4 v[214:215], off
	s_waitcnt vmcnt(8)
	s_waitcnt lgkmcnt(0)
	s_barrier
	v_mfma_f32_16x16x32_bf16 v[62:65], v[148:151], v[182:185], v[62:65]
	v_mfma_f32_16x16x32_bf16 v[58:61], v[156:159], v[182:185], v[58:61]
	v_mfma_f32_16x16x32_bf16 v[46:49], v[148:151], v[190:193], v[46:49]
	v_mfma_f32_16x16x32_bf16 v[42:45], v[156:159], v[190:193], v[42:45]
	v_mfma_f32_16x16x32_bf16 v[30:33], v[148:151], v[198:201], v[30:33]
	v_mfma_f32_16x16x32_bf16 v[26:29], v[156:159], v[198:201], v[26:29]
	v_mfma_f32_16x16x32_bf16 v[14:17], v[148:151], v[206:209], v[14:17]
	v_mfma_f32_16x16x32_bf16 v[10:13], v[156:159], v[206:209], v[10:13]
	v_mfma_f32_16x16x32_bf16 v[62:65], v[152:155], v[186:189], v[62:65]
	v_mfma_f32_16x16x32_bf16 v[58:61], v[160:163], v[186:189], v[58:61]
	v_mfma_f32_16x16x32_bf16 v[46:49], v[152:155], v[194:197], v[46:49]
	v_mfma_f32_16x16x32_bf16 v[42:45], v[160:163], v[194:197], v[42:45]
	v_mfma_f32_16x16x32_bf16 v[30:33], v[152:155], v[202:205], v[30:33]
	v_mfma_f32_16x16x32_bf16 v[26:29], v[160:163], v[202:205], v[26:29]
	v_mfma_f32_16x16x32_bf16 v[14:17], v[152:155], v[210:213], v[14:17]
	v_mfma_f32_16x16x32_bf16 v[10:13], v[160:163], v[210:213], v[10:13]
	v_mfma_f32_16x16x32_bf16 v[54:57], v[164:167], v[182:185], v[54:57]
	v_mfma_f32_16x16x32_bf16 v[50:53], v[172:175], v[182:185], v[50:53]
	v_mfma_f32_16x16x32_bf16 v[38:41], v[164:167], v[190:193], v[38:41]
	v_mfma_f32_16x16x32_bf16 v[34:37], v[172:175], v[190:193], v[34:37]
	v_mfma_f32_16x16x32_bf16 v[22:25], v[164:167], v[198:201], v[22:25]
	v_mfma_f32_16x16x32_bf16 v[18:21], v[172:175], v[198:201], v[18:21]
	v_mfma_f32_16x16x32_bf16 v[6:9], v[164:167], v[206:209], v[6:9]
	v_mfma_f32_16x16x32_bf16 v[2:5], v[172:175], v[206:209], v[2:5]
	v_mfma_f32_16x16x32_bf16 v[54:57], v[168:171], v[186:189], v[54:57]
	v_mfma_f32_16x16x32_bf16 v[50:53], v[176:179], v[186:189], v[50:53]
	v_mfma_f32_16x16x32_bf16 v[38:41], v[168:171], v[194:197], v[38:41]
	v_mfma_f32_16x16x32_bf16 v[34:37], v[176:179], v[194:197], v[34:37]
	v_mfma_f32_16x16x32_bf16 v[22:25], v[168:171], v[202:205], v[22:25]
	v_mfma_f32_16x16x32_bf16 v[18:21], v[176:179], v[202:205], v[18:21]
	v_mfma_f32_16x16x32_bf16 v[6:9], v[168:171], v[210:213], v[6:9]
	v_mfma_f32_16x16x32_bf16 v[2:5], v[176:179], v[210:213], v[2:5]
	s_barrier
	s_add_i32 s50, s50, 2
	s_add_u32 s20, s20, 0x100
	s_addc_u32 s21, s21, 0
	s_add_u32 s48, s48, 0x100
	s_addc_u32 s49, s49, 0
	s_cmp_gt_u32 s50, 13
	s_cbranch_scc0 .LBB0_1550
	s_and_b64 vcc, exec, s[10:11]
	s_cbranch_vccz .LBB0_1553
	s_barrier

; #define PG8_STAGE(bufoff, gbase, voff) do { _Pragma("unroll") for (int _i = 0; _i < 2; ++_i) \
;         __builtin_amdgcn_global_load_lds((const unsigned*)((const char*)(gbase) + (voff)[_i]), (LAS unsigned*)(lds + (bufoff) + ldsw + _i * 8192), 16, 0, 0); } while (0)
; #define PG8_LDA(dst, b, h) do { _Pragma("unroll") for (int m = 0; m < 4; ++m) _Pragma("unroll") for (int k = 0; k < 2; ++k) dst[m][k] = *(const LAS bf16x8*)(lds + PG8_SA(b, h) + aoff + m * 2048 + k * 1024); } while (0)
; #define PG8_LDB(dst, b, h) do { _Pragma("unroll") for (int n = 0; n < 2; ++n) _Pragma("unroll") for (int k = 0; k < 2; ++k) dst[n][k] = *(const LAS bf16x8*)(lds + PG8_SB(b, h) + boff + n * 2048 + k * 1024); } while (0)
; #define PG8_MMA(ai, bj, At, Bt) do { __builtin_amdgcn_s_setprio(1); _Pragma("unroll") for (int m = 0; m < 4; ++m) _Pragma("unroll") for (int n = 0; n < 2; ++n) _Pragma("unroll") for (int k = 0; k < 2; ++k) \
;         acc[ai][bj][m][n] = __builtin_amdgcn_mfma_f32_16x16x32_bf16(Bt[n][k], At[m][k], acc[ai][bj][m][n], 0, 0, 0); __builtin_amdgcn_s_setprio(0); } while (0)
; #define PG8_WAIT_V(n) asm volatile("s_waitcnt vmcnt(" #n ")" ::: "memory")
; #define PG8_WAIT_L(n) asm volatile("s_waitcnt lgkmcnt(" #n ")" ::: "memory")
; #define PG8_BAR __builtin_amdgcn_s_barrier()
; #define PG8_SCHED __builtin_amdgcn_sched_barrier(0)
; template <class Epi>
; __device__ __forceinline__ void gemm_phase(LAS unsigned char* lds, const Gemm g, const StaticOrder& S, const Epi& E) {
;     ...
;             PG8_LDB(B0, 0, 0); PG8_LDB(B1, 0, 1); PG8_SCHED; PG8_LDA(At, 0, 0); PG8_STAGE(PG8_SA(1, 1), a1 + hA, voffA);
;             PG8_WAIT_V(8); PG8_WAIT_L(0); PG8_BAR; PG8_MMA(0, 0, At, B0); PG8_MMA(0, 1, At, B1); PG8_BAR; PG8_SCHED;
;             PG8_LDA(At, 0, 1); PG8_STAGE(PG8_SB(0, 0), b2, voffB); PG8_STAGE(PG8_SB(0, 1), b2 + hB, voffB); PG8_STAGE(PG8_SA(0, 0), a2, voffA);
;             PG8_WAIT_V(8); PG8_WAIT_L(0); PG8_BAR; PG8_MMA(1, 0, At, B0); PG8_MMA(1, 1, At, B1); PG8_BAR; PG8_SCHED;
.LBB0_1632:
	s_add_u32 s8, s10, 0x100
	s_addc_u32 s9, s11, 0
	s_add_i32 s70, 0, 0x10000
	s_cmp_eq_u32 s67, 40
	s_cselect_b32 s45, s39, s9
	s_cselect_b32 s44, s38, s8
	s_cselect_b32 s43, s41, s37
	s_cselect_b32 s42, s40, s35
	s_add_i32 s71, 0, 0x14000
	s_waitcnt lgkmcnt(0)
	v_add_u32_e32 v158, s70, v180
	v_add_u32_e32 v174, s71, v180
	ds_read_b128 v[146:149], v158
	ds_read_b128 v[150:153], v158 offset:1024
	ds_read_b128 v[154:157], v158 offset:2048
	ds_read_b128 v[158:161], v158 offset:3072
	ds_read_b128 v[162:165], v174
	ds_read_b128 v[166:169], v174 offset:1024
	ds_read_b128 v[170:173], v174 offset:2048
	ds_read_b128 v[174:177], v174 offset:3072
	v_lshl_add_u64 v[178:179], s[10:11], 0, v[142:143]
	s_add_i32 m0, s52, 0xc000
	ds_read_b128 v[182:185], v192
	ds_read_b128 v[196:199], v192 offset:1024
	ds_read_b128 v[200:203], v192 offset:2048
	ds_read_b128 v[204:207], v192 offset:3072
	ds_read_b128 v[208:211], v192 offset:4096
	ds_read_b128 v[212:215], v192 offset:5120
	ds_read_b128 v[216:219], v192 offset:6144
	ds_read_b128 v[232:235], v192 offset:7168
	global_load_lds_dwordx4 v[178:179], off
	v_lshl_add_u64 v[178:179], s[10:11], 0, v[144:145]
	s_add_i32 m0, s52, 0xe000
	s_nop 0
	global_load_lds_dwordx4 v[178:179], off
	s_waitcnt vmcnt(8)
	s_waitcnt lgkmcnt(0)
	s_barrier
	v_mfma_f32_16x16x32_bf16 v[26:29], v[146:149], v[182:185], v[26:29]
	v_mfma_f32_16x16x32_bf16 v[30:33], v[154:157], v[182:185], v[30:33]
	v_mfma_f32_16x16x32_bf16 v[58:61], v[146:149], v[200:203], v[58:61]
	v_mfma_f32_16x16x32_bf16 v[62:65], v[154:157], v[200:203], v[62:65]
	v_mfma_f32_16x16x32_bf16 v[90:93], v[146:149], v[208:211], v[90:93]
	v_mfma_f32_16x16x32_bf16 v[94:97], v[154:157], v[208:211], v[94:97]
	v_mfma_f32_16x16x32_bf16 v[114:117], v[146:149], v[216:219], v[114:117]
	v_mfma_f32_16x16x32_bf16 v[118:121], v[154:157], v[216:219], v[118:121]
	v_mfma_f32_16x16x32_bf16 v[26:29], v[150:153], v[196:199], v[26:29]
	v_mfma_f32_16x16x32_bf16 v[30:33], v[158:161], v[196:199], v[30:33]
	v_mfma_f32_16x16x32_bf16 v[58:61], v[150:153], v[204:207], v[58:61]
	v_mfma_f32_16x16x32_bf16 v[62:65], v[158:161], v[204:207], v[62:65]
	v_mfma_f32_16x16x32_bf16 v[90:93], v[150:153], v[212:215], v[90:93]
	v_mfma_f32_16x16x32_bf16 v[94:97], v[158:161], v[212:215], v[94:97]
	v_mfma_f32_16x16x32_bf16 v[114:117], v[150:153], v[232:235], v[114:117]
	v_mfma_f32_16x16x32_bf16 v[118:121], v[158:161], v[232:235], v[118:121]
	v_mfma_f32_16x16x32_bf16 v[42:45], v[162:165], v[182:185], v[42:45]
	v_mfma_f32_16x16x32_bf16 v[46:49], v[170:173], v[182:185], v[46:49]
	v_mfma_f32_16x16x32_bf16 v[74:77], v[162:165], v[200:203], v[74:77]
	v_mfma_f32_16x16x32_bf16 v[78:81], v[170:173], v[200:203], v[78:81]
	v_mfma_f32_16x16x32_bf16 v[106:109], v[162:165], v[208:211], v[106:109]
	v_mfma_f32_16x16x32_bf16 v[110:113], v[170:173], v[208:211], v[110:113]
	v_mfma_f32_16x16x32_bf16 v[126:129], v[162:165], v[216:219], v[126:129]
	v_mfma_f32_16x16x32_bf16 v[122:125], v[170:173], v[216:219], v[122:125]
	v_mfma_f32_16x16x32_bf16 v[42:45], v[166:169], v[196:199], v[42:45]
	v_mfma_f32_16x16x32_bf16 v[46:49], v[174:177], v[196:199], v[46:49]
	v_mfma_f32_16x16x32_bf16 v[74:77], v[166:169], v[204:207], v[74:77]
	v_mfma_f32_16x16x32_bf16 v[78:81], v[174:177], v[204:207], v[78:81]
	v_mfma_f32_16x16x32_bf16 v[106:109], v[166:169], v[212:215], v[106:109]
	v_mfma_f32_16x16x32_bf16 v[110:113], v[174:177], v[212:215], v[110:113]
	v_mfma_f32_16x16x32_bf16 v[126:129], v[166:169], v[232:235], v[126:129]
	v_mfma_f32_16x16x32_bf16 v[122:125], v[174:177], v[232:235], v[122:125]
	s_barrier
	s_add_i32 s10, s70, s47
	v_lshl_add_u64 v[178:179], s[42:43], 0, v[132:133]
	s_mov_b32 m0, s10
	ds_read_b128 v[182:185], v192 offset:16384
	ds_read_b128 v[196:199], v192 offset:17408
	ds_read_b128 v[200:203], v192 offset:18432
	ds_read_b128 v[204:207], v192 offset:19456
	ds_read_b128 v[208:211], v192 offset:20480
	ds_read_b128 v[212:215], v192 offset:21504
	ds_read_b128 v[216:219], v192 offset:22528
	ds_read_b128 v[232:235], v192 offset:23552
	global_load_lds_dwordx4 v[178:179], off
	s_add_i32 m0, s10, 0x2000
	s_add_u32 s10, s42, 0xb0000
	v_lshl_add_u64 v[186:187], s[42:43], 0, v[136:137]
	s_addc_u32 s11, s43, 0
	s_add_i32 s70, s71, s47
	global_load_lds_dwordx4 v[186:187], off
	v_lshl_add_u64 v[220:221], s[10:11], 0, v[132:133]
	s_mov_b32 m0, s70
	v_lshl_add_u64 v[236:237], s[44:45], 0, v[134:135]
	global_load_lds_dwordx4 v[220:221], off
	v_lshl_add_u64 v[220:221], s[10:11], 0, v[136:137]
	s_add_i32 m0, s70, 0x2000
	s_nop 0
	global_load_lds_dwordx4 v[220:221], off
	v_lshl_add_u64 v[220:221], s[44:45], 0, v[130:131]
	s_mov_b32 m0, s52
	s_nop 0
	global_load_lds_dwordx4 v[220:221], off
	s_mov_b32 m0, s53
	s_nop 0
	global_load_lds_dwordx4 v[236:237], off
	s_waitcnt vmcnt(8)
	s_waitcnt lgkmcnt(0)
	s_barrier
; #define PG8_STAGE(bufoff, gbase, voff) do { _Pragma("unroll") for (int _i = 0; _i < 2; ++_i) \
;         __builtin_amdgcn_global_load_lds((const unsigned*)((const char*)(gbase) + (voff)[_i]), (LAS unsigned*)(lds + (bufoff) + ldsw + _i * 8192), 16, 0, 0); } while (0)
; #define PG8_LDA(dst, b, h) do { _Pragma("unroll") for (int m = 0; m < 4; ++m) _Pragma("unroll") for (int k = 0; k < 2; ++k) dst[m][k] = *(const LAS bf16x8*)(lds + PG8_SA(b, h) + aoff + m * 2048 + k * 1024); } while (0)
; #define PG8_LDB(dst, b, h) do { _Pragma("unroll") for (int n = 0; n < 2; ++n) _Pragma("unroll") for (int k = 0; k < 2; ++k) dst[n][k] = *(const LAS bf16x8*)(lds + PG8_SB(b, h) + boff + n * 2048 + k * 1024); } while (0)
; #define PG8_MMA(ai, bj, At, Bt) do { __builtin_amdgcn_s_setprio(1); _Pragma("unroll") for (int m = 0; m < 4; ++m) _Pragma("unroll") for (int n = 0; n < 2; ++n) _Pragma("unroll") for (int k = 0; k < 2; ++k) \
;         acc[ai][bj][m][n] = __builtin_amdgcn_mfma_f32_16x16x32_bf16(Bt[n][k], At[m][k], acc[ai][bj][m][n], 0, 0, 0); __builtin_amdgcn_s_setprio(0); } while (0)
; #define PG8_WAIT_V(n) asm volatile("s_waitcnt vmcnt(" #n ")" ::: "memory")
; #define PG8_WAIT_L(n) asm volatile("s_waitcnt lgkmcnt(" #n ")" ::: "memory")
; #define PG8_BAR __builtin_amdgcn_s_barrier()
; #define PG8_SCHED __builtin_amdgcn_sched_barrier(0)
; template <class Epi>
; __device__ __forceinline__ void gemm_phase(LAS unsigned char* lds, const Gemm g, const StaticOrder& S, const Epi& E) {
;     ...
;             PG8_WAIT_V(8); PG8_WAIT_L(0); PG8_BAR; PG8_MMA(0, 0, At, B0); PG8_MMA(0, 1, At, B1); PG8_BAR; PG8_SCHED;
;             PG8_LDA(At, 0, 1); PG8_STAGE(PG8_SB(0, 0), b2, voffB); PG8_STAGE(PG8_SB(0, 1), b2 + hB, voffB); PG8_STAGE(PG8_SA(0, 0), a2, voffA);
;             PG8_WAIT_V(8); PG8_WAIT_L(0); PG8_BAR; PG8_MMA(1, 0, At, B0); PG8_MMA(1, 1, At, B1); PG8_BAR; PG8_SCHED;
;             PG8_LDB(B0, 1, 0); PG8_LDB(B1, 1, 1); PG8_SCHED; PG8_LDA(At, 1, 0); PG8_STAGE(PG8_SA(0, 1), a2 + hA, voffA);
;             PG8_WAIT_V(8); PG8_WAIT_L(0); PG8_BAR; PG8_MMA(0, 0, At, B0); PG8_MMA(0, 1, At, B1); PG8_BAR; PG8_SCHED;
	v_mfma_f32_16x16x32_bf16 v[102:105], v[146:149], v[182:185], v[102:105]
	v_mfma_f32_16x16x32_bf16 v[98:101], v[154:157], v[182:185], v[98:101]
	v_mfma_f32_16x16x32_bf16 v[70:73], v[146:149], v[200:203], v[70:73]
	v_mfma_f32_16x16x32_bf16 v[66:69], v[154:157], v[200:203], v[66:69]
	v_mfma_f32_16x16x32_bf16 v[38:41], v[146:149], v[208:211], v[38:41]
	v_mfma_f32_16x16x32_bf16 v[34:37], v[154:157], v[208:211], v[34:37]
	v_mfma_f32_16x16x32_bf16 v[14:17], v[146:149], v[216:219], v[14:17]
	v_mfma_f32_16x16x32_bf16 v[10:13], v[154:157], v[216:219], v[10:13]
	v_mfma_f32_16x16x32_bf16 v[102:105], v[150:153], v[196:199], v[102:105]
	v_mfma_f32_16x16x32_bf16 v[98:101], v[158:161], v[196:199], v[98:101]
	v_mfma_f32_16x16x32_bf16 v[70:73], v[150:153], v[204:207], v[70:73]
	v_mfma_f32_16x16x32_bf16 v[66:69], v[158:161], v[204:207], v[66:69]
	v_mfma_f32_16x16x32_bf16 v[38:41], v[150:153], v[212:215], v[38:41]
	v_mfma_f32_16x16x32_bf16 v[34:37], v[158:161], v[212:215], v[34:37]
	v_mfma_f32_16x16x32_bf16 v[14:17], v[150:153], v[232:235], v[14:17]
	v_mfma_f32_16x16x32_bf16 v[10:13], v[158:161], v[232:235], v[10:13]
	v_mfma_f32_16x16x32_bf16 v[86:89], v[162:165], v[182:185], v[86:89]
	v_mfma_f32_16x16x32_bf16 v[82:85], v[170:173], v[182:185], v[82:85]
	v_mfma_f32_16x16x32_bf16 v[54:57], v[162:165], v[200:203], v[54:57]
	v_mfma_f32_16x16x32_bf16 v[50:53], v[170:173], v[200:203], v[50:53]
	v_mfma_f32_16x16x32_bf16 v[22:25], v[162:165], v[208:211], v[22:25]
	v_mfma_f32_16x16x32_bf16 v[18:21], v[170:173], v[208:211], v[18:21]
	v_mfma_f32_16x16x32_bf16 v[6:9], v[162:165], v[216:219], v[6:9]
	v_mfma_f32_16x16x32_bf16 v[2:5], v[170:173], v[216:219], v[2:5]
	v_mfma_f32_16x16x32_bf16 v[86:89], v[166:169], v[196:199], v[86:89]
	v_mfma_f32_16x16x32_bf16 v[82:85], v[174:177], v[196:199], v[82:85]
	v_mfma_f32_16x16x32_bf16 v[54:57], v[166:169], v[204:207], v[54:57]
	v_mfma_f32_16x16x32_bf16 v[50:53], v[174:177], v[204:207], v[50:53]
	v_mfma_f32_16x16x32_bf16 v[22:25], v[166:169], v[212:215], v[22:25]
	v_mfma_f32_16x16x32_bf16 v[18:21], v[174:177], v[212:215], v[18:21]
	v_mfma_f32_16x16x32_bf16 v[6:9], v[166:169], v[232:235], v[6:9]
	v_mfma_f32_16x16x32_bf16 v[2:5], v[174:177], v[232:235], v[2:5]
	s_barrier
	s_add_i32 s70, 0, 0x18000
	s_add_i32 s71, 0, 0x1c000
	v_add_u32_e32 v158, s70, v180
	v_add_u32_e32 v174, s71, v180
	ds_read_b128 v[146:149], v158
	ds_read_b128 v[150:153], v158 offset:1024
	ds_read_b128 v[154:157], v158 offset:2048
	ds_read_b128 v[158:161], v158 offset:3072
	ds_read_b128 v[162:165], v174
	ds_read_b128 v[166:169], v174 offset:1024
	ds_read_b128 v[170:173], v174 offset:2048
	ds_read_b128 v[174:177], v174 offset:3072
	s_add_u32 s10, s44, 0xb0000
	s_addc_u32 s11, s45, 0
	s_mov_b32 m0, s54
	v_lshl_add_u64 v[238:239], s[10:11], 0, v[130:131]
	ds_read_b128 v[182:185], v192 offset:32768
	ds_read_b128 v[196:199], v192 offset:33792
	ds_read_b128 v[200:203], v192 offset:34816
	ds_read_b128 v[204:207], v192 offset:35840
	ds_read_b128 v[208:211], v192 offset:36864
	ds_read_b128 v[212:215], v192 offset:37888
	ds_read_b128 v[216:219], v192 offset:38912
	ds_read_b128 v[232:235], v192 offset:39936
	global_load_lds_dwordx4 v[238:239], off
	v_lshl_add_u64 v[238:239], s[10:11], 0, v[134:135]
	s_mov_b32 m0, s55
	s_nop 0
	global_load_lds_dwordx4 v[238:239], off
	s_waitcnt vmcnt(8)
	s_waitcnt lgkmcnt(0)
	s_barrier
	v_mfma_f32_16x16x32_bf16 v[26:29], v[146:149], v[182:185], v[26:29]
	v_mfma_f32_16x16x32_bf16 v[30:33], v[154:157], v[182:185], v[30:33]
	v_mfma_f32_16x16x32_bf16 v[58:61], v[146:149], v[200:203], v[58:61]
	v_mfma_f32_16x16x32_bf16 v[62:65], v[154:157], v[200:203], v[62:65]
	v_mfma_f32_16x16x32_bf16 v[90:93], v[146:149], v[208:211], v[90:93]
	v_mfma_f32_16x16x32_bf16 v[94:97], v[154:157], v[208:211], v[94:97]
	v_mfma_f32_16x16x32_bf16 v[114:117], v[146:149], v[216:219], v[114:117]
	v_mfma_f32_16x16x32_bf16 v[118:121], v[154:157], v[216:219], v[118:121]
	v_mfma_f32_16x16x32_bf16 v[26:29], v[150:153], v[196:199], v[26:29]
	v_mfma_f32_16x16x32_bf16 v[30:33], v[158:161], v[196:199], v[30:33]
	v_mfma_f32_16x16x32_bf16 v[58:61], v[150:153], v[204:207], v[58:61]
	v_mfma_f32_16x16x32_bf16 v[62:65], v[158:161], v[204:207], v[62:65]
	v_mfma_f32_16x16x32_bf16 v[90:93], v[150:153], v[212:215], v[90:93]
	v_mfma_f32_16x16x32_bf16 v[94:97], v[158:161], v[212:215], v[94:97]
	v_mfma_f32_16x16x32_bf16 v[114:117], v[150:153], v[232:235], v[114:117]
	v_mfma_f32_16x16x32_bf16 v[118:121], v[158:161], v[232:235], v[118:121]
	v_mfma_f32_16x16x32_bf16 v[42:45], v[162:165], v[182:185], v[42:45]
	v_mfma_f32_16x16x32_bf16 v[46:49], v[170:173], v[182:185], v[46:49]
	v_mfma_f32_16x16x32_bf16 v[74:77], v[162:165], v[200:203], v[74:77]
	v_mfma_f32_16x16x32_bf16 v[78:81], v[170:173], v[200:203], v[78:81]
	v_mfma_f32_16x16x32_bf16 v[106:109], v[162:165], v[208:211], v[106:109]
	v_mfma_f32_16x16x32_bf16 v[110:113], v[170:173], v[208:211], v[110:113]
	v_mfma_f32_16x16x32_bf16 v[126:129], v[162:165], v[216:219], v[126:129]
	v_mfma_f32_16x16x32_bf16 v[122:125], v[170:173], v[216:219], v[122:125]
	v_mfma_f32_16x16x32_bf16 v[42:45], v[166:169], v[196:199], v[42:45]
	v_mfma_f32_16x16x32_bf16 v[46:49], v[174:177], v[196:199], v[46:49]
	v_mfma_f32_16x16x32_bf16 v[74:77], v[166:169], v[204:207], v[74:77]
	v_mfma_f32_16x16x32_bf16 v[78:81], v[174:177], v[204:207], v[78:81]
	v_mfma_f32_16x16x32_bf16 v[106:109], v[166:169], v[212:215], v[106:109]
	v_mfma_f32_16x16x32_bf16 v[110:113], v[174:177], v[212:215], v[110:113]
	v_mfma_f32_16x16x32_bf16 v[126:129], v[166:169], v[232:235], v[126:129]
	v_mfma_f32_16x16x32_bf16 v[122:125], v[174:177], v[232:235], v[122:125]
	s_barrier
; #define PG8_STAGE(bufoff, gbase, voff) do { _Pragma("unroll") for (int _i = 0; _i < 2; ++_i) \
;         __builtin_amdgcn_global_load_lds((const unsigned*)((const char*)(gbase) + (voff)[_i]), (LAS unsigned*)(lds + (bufoff) + ldsw + _i * 8192), 16, 0, 0); } while (0)
; #define PG8_LDA(dst, b, h) do { _Pragma("unroll") for (int m = 0; m < 4; ++m) _Pragma("unroll") for (int k = 0; k < 2; ++k) dst[m][k] = *(const LAS bf16x8*)(lds + PG8_SA(b, h) + aoff + m * 2048 + k * 1024); } while (0)
; #define PG8_MMA(ai, bj, At, Bt) do { __builtin_amdgcn_s_setprio(1); _Pragma("unroll") for (int m = 0; m < 4; ++m) _Pragma("unroll") for (int n = 0; n < 2; ++n) _Pragma("unroll") for (int k = 0; k < 2; ++k) \
;         acc[ai][bj][m][n] = __builtin_amdgcn_mfma_f32_16x16x32_bf16(Bt[n][k], At[m][k], acc[ai][bj][m][n], 0, 0, 0); __builtin_amdgcn_s_setprio(0); } while (0)
; #define PG8_WAIT_V(n) asm volatile("s_waitcnt vmcnt(" #n ")" ::: "memory")
; #define PG8_WAIT_L(n) asm volatile("s_waitcnt lgkmcnt(" #n ")" ::: "memory")
; #define PG8_BAR __builtin_amdgcn_s_barrier()
; #define PG8_SCHED __builtin_amdgcn_sched_barrier(0)
; template <class Epi>
; __device__ __forceinline__ void gemm_phase(LAS unsigned char* lds, const Gemm g, const StaticOrder& S, const Epi& E) {
;     ...
;             PG8_LDA(At, 1, 1); PG8_STAGE(PG8_SB(1, 0), b3, voffB); PG8_STAGE(PG8_SB(1, 1), b3 + hB, voffB); PG8_STAGE(PG8_SA(1, 0), a3, voffA);
;             PG8_WAIT_V(8); PG8_WAIT_L(0); PG8_BAR; PG8_MMA(1, 0, At, B0); PG8_MMA(1, 1, At, B1); PG8_BAR; PG8_SCHED;
;         }
;         if (wr == 0) PG8_BAR;
	s_add_i32 s10, s70, s47
	v_lshl_add_u64 v[178:179], v[178:179], 0, s[88:89]
	s_mov_b32 m0, s10
	ds_read_b128 v[182:185], v192 offset:49152
	ds_read_b128 v[196:199], v192 offset:50176
	ds_read_b128 v[200:203], v192 offset:51200
	ds_read_b128 v[204:207], v192 offset:52224
	ds_read_b128 v[208:211], v192 offset:53248
	ds_read_b128 v[212:215], v192 offset:54272
	ds_read_b128 v[216:219], v192 offset:55296
	ds_read_b128 v[232:235], v192 offset:56320
	global_load_lds_dwordx4 v[178:179], off
	s_add_i32 m0, s10, 0x2000
	s_add_u32 s10, s42, 0xb0080
	v_lshl_add_u64 v[178:179], v[186:187], 0, s[88:89]
	s_addc_u32 s11, s43, 0
	s_add_i32 s42, s71, s47
	global_load_lds_dwordx4 v[178:179], off
	v_lshl_add_u64 v[178:179], s[10:11], 0, v[132:133]
	s_mov_b32 m0, s42
	s_nop 0
	global_load_lds_dwordx4 v[178:179], off
	v_lshl_add_u64 v[178:179], s[10:11], 0, v[136:137]
	s_add_i32 m0, s42, 0x2000
	s_nop 0
	global_load_lds_dwordx4 v[178:179], off
	v_lshl_add_u64 v[178:179], v[220:221], 0, s[88:89]
	s_mov_b32 m0, s56
	s_nop 0
	global_load_lds_dwordx4 v[178:179], off
	v_lshl_add_u64 v[178:179], v[236:237], 0, s[88:89]
	s_mov_b32 m0, s57
	s_nop 0
	global_load_lds_dwordx4 v[178:179], off
	s_waitcnt vmcnt(8)
	s_waitcnt lgkmcnt(0)
	s_barrier
	v_mfma_f32_16x16x32_bf16 v[102:105], v[146:149], v[182:185], v[102:105]
	v_mfma_f32_16x16x32_bf16 v[98:101], v[154:157], v[182:185], v[98:101]
	v_mfma_f32_16x16x32_bf16 v[70:73], v[146:149], v[200:203], v[70:73]
	v_mfma_f32_16x16x32_bf16 v[66:69], v[154:157], v[200:203], v[66:69]
	v_mfma_f32_16x16x32_bf16 v[38:41], v[146:149], v[208:211], v[38:41]
	v_mfma_f32_16x16x32_bf16 v[34:37], v[154:157], v[208:211], v[34:37]
	v_mfma_f32_16x16x32_bf16 v[14:17], v[146:149], v[216:219], v[14:17]
	v_mfma_f32_16x16x32_bf16 v[10:13], v[154:157], v[216:219], v[10:13]
	v_mfma_f32_16x16x32_bf16 v[102:105], v[150:153], v[196:199], v[102:105]
	v_mfma_f32_16x16x32_bf16 v[98:101], v[158:161], v[196:199], v[98:101]
	v_mfma_f32_16x16x32_bf16 v[70:73], v[150:153], v[204:207], v[70:73]
	v_mfma_f32_16x16x32_bf16 v[66:69], v[158:161], v[204:207], v[66:69]
	v_mfma_f32_16x16x32_bf16 v[38:41], v[150:153], v[212:215], v[38:41]
	v_mfma_f32_16x16x32_bf16 v[34:37], v[158:161], v[212:215], v[34:37]
	v_mfma_f32_16x16x32_bf16 v[14:17], v[150:153], v[232:235], v[14:17]
	v_mfma_f32_16x16x32_bf16 v[10:13], v[158:161], v[232:235], v[10:13]
	v_mfma_f32_16x16x32_bf16 v[86:89], v[162:165], v[182:185], v[86:89]
	v_mfma_f32_16x16x32_bf16 v[82:85], v[170:173], v[182:185], v[82:85]
	v_mfma_f32_16x16x32_bf16 v[54:57], v[162:165], v[200:203], v[54:57]
	v_mfma_f32_16x16x32_bf16 v[50:53], v[170:173], v[200:203], v[50:53]
	v_mfma_f32_16x16x32_bf16 v[22:25], v[162:165], v[208:211], v[22:25]
	v_mfma_f32_16x16x32_bf16 v[18:21], v[170:173], v[208:211], v[18:21]
	v_mfma_f32_16x16x32_bf16 v[6:9], v[162:165], v[216:219], v[6:9]
	v_mfma_f32_16x16x32_bf16 v[2:5], v[170:173], v[216:219], v[2:5]
	v_mfma_f32_16x16x32_bf16 v[86:89], v[166:169], v[196:199], v[86:89]
	v_mfma_f32_16x16x32_bf16 v[82:85], v[174:177], v[196:199], v[82:85]
	v_mfma_f32_16x16x32_bf16 v[54:57], v[166:169], v[204:207], v[54:57]
	v_mfma_f32_16x16x32_bf16 v[50:53], v[174:177], v[204:207], v[50:53]
	v_mfma_f32_16x16x32_bf16 v[22:25], v[166:169], v[212:215], v[22:25]
	v_mfma_f32_16x16x32_bf16 v[18:21], v[174:177], v[212:215], v[18:21]
	v_mfma_f32_16x16x32_bf16 v[6:9], v[166:169], v[232:235], v[6:9]
	v_mfma_f32_16x16x32_bf16 v[2:5], v[174:177], v[232:235], v[2:5]
	s_barrier
	s_add_i32 s67, s67, 2
	s_add_u32 s35, s35, 0x100
	s_addc_u32 s37, s37, 0
	s_cmp_gt_u32 s67, 41
	s_mov_b64 s[10:11], s[8:9]
	s_cbranch_scc0 .LBB0_1632
	s_and_b64 vcc, exec, s[20:21]
	s_cbranch_vccz .LBB0_1635
	s_barrier
